# GEMM K loops: back edge rotated - counter/pointer updates, next iteration's base selection and the exit test moved to the end of the last load segment; only the branch remains behind the closing barri
# speedup vs baseline: 1.0046x; 1.0046x over previous
.LBB0_31:
	s_add_u32 s40, s12, 0x100
	v_mov_b32_e32 v0, 0
	s_addc_u32 s41, s13, 0
	s_mov_b32 s42, -2
	v_mov_b32_e32 v1, v0
	v_mov_b32_e32 v2, v0
	v_mov_b32_e32 v3, v0
	v_mov_b32_e32 v26, v0
	v_mov_b32_e32 v27, v0
	v_mov_b32_e32 v28, v0
	v_mov_b32_e32 v29, v0
	v_mov_b32_e32 v4, v0
	v_mov_b32_e32 v5, v0
	v_mov_b32_e32 v6, v0
	v_mov_b32_e32 v7, v0
	v_mov_b32_e32 v34, v0
	v_mov_b32_e32 v35, v0
	v_mov_b32_e32 v36, v0
	v_mov_b32_e32 v37, v0
	v_mov_b32_e32 v8, v0
	v_mov_b32_e32 v9, v0
	v_mov_b32_e32 v10, v0
	v_mov_b32_e32 v11, v0
	v_mov_b32_e32 v38, v0
	v_mov_b32_e32 v39, v0
	v_mov_b32_e32 v40, v0
	v_mov_b32_e32 v41, v0
	v_mov_b32_e32 v12, v0
	v_mov_b32_e32 v13, v0
	v_mov_b32_e32 v14, v0
	v_mov_b32_e32 v15, v0
	v_mov_b32_e32 v46, v0
	v_mov_b32_e32 v47, v0
	v_mov_b32_e32 v48, v0
	v_mov_b32_e32 v49, v0
	v_mov_b32_e32 v62, v0
	v_mov_b32_e32 v63, v0
	v_mov_b32_e32 v64, v0
	v_mov_b32_e32 v65, v0
	v_mov_b32_e32 v98, v0
	v_mov_b32_e32 v99, v0
	v_mov_b32_e32 v100, v0
	v_mov_b32_e32 v101, v0
	s_waitcnt vmcnt(0)
	v_mov_b32_e32 v70, v0
	v_mov_b32_e32 v71, v0
	v_mov_b32_e32 v72, v0
	v_mov_b32_e32 v73, v0
	v_mov_b32_e32 v102, v0
	v_mov_b32_e32 v103, v0
	v_mov_b32_e32 v104, v0
	v_mov_b32_e32 v105, v0
	v_mov_b32_e32 v74, v0
	v_mov_b32_e32 v75, v0
	v_mov_b32_e32 v76, v0
	v_mov_b32_e32 v77, v0
	v_mov_b32_e32 v106, v0
	v_mov_b32_e32 v107, v0
	v_mov_b32_e32 v108, v0
	v_mov_b32_e32 v109, v0
	v_mov_b32_e32 v78, v0
	v_mov_b32_e32 v79, v0
	v_mov_b32_e32 v80, v0
	v_mov_b32_e32 v81, v0
	v_mov_b32_e32 v110, v0
	v_mov_b32_e32 v111, v0
	v_mov_b32_e32 v112, v0
	v_mov_b32_e32 v113, v0
	v_mov_b32_e32 v18, v0
	v_mov_b32_e32 v19, v0
	v_mov_b32_e32 v20, v0
	v_mov_b32_e32 v21, v0
	v_mov_b32_e32 v50, v0
	v_mov_b32_e32 v51, v0
	v_mov_b32_e32 v52, v0
	v_mov_b32_e32 v53, v0
	v_mov_b32_e32 v22, v0
	v_mov_b32_e32 v23, v0
	v_mov_b32_e32 v24, v0
	v_mov_b32_e32 v25, v0
	v_mov_b32_e32 v54, v0
	v_mov_b32_e32 v55, v0
	v_mov_b32_e32 v56, v0
	v_mov_b32_e32 v57, v0
	v_mov_b32_e32 v30, v0
	v_mov_b32_e32 v31, v0
	v_mov_b32_e32 v32, v0
	v_mov_b32_e32 v33, v0
	v_mov_b32_e32 v58, v0
	v_mov_b32_e32 v59, v0
	v_mov_b32_e32 v60, v0
	v_mov_b32_e32 v61, v0
	v_mov_b32_e32 v42, v0
	v_mov_b32_e32 v43, v0
	v_mov_b32_e32 v44, v0
	v_mov_b32_e32 v45, v0
	v_mov_b32_e32 v66, v0
	v_mov_b32_e32 v67, v0
	v_mov_b32_e32 v68, v0
	v_mov_b32_e32 v69, v0
	v_mov_b32_e32 v82, v0
	v_mov_b32_e32 v83, v0
	v_mov_b32_e32 v84, v0
	v_mov_b32_e32 v85, v0
	v_mov_b32_e32 v114, v0
	v_mov_b32_e32 v115, v0
	v_mov_b32_e32 v116, v0
	v_mov_b32_e32 v117, v0
	v_mov_b32_e32 v86, v0
	v_mov_b32_e32 v87, v0
	v_mov_b32_e32 v88, v0
	v_mov_b32_e32 v89, v0
	v_mov_b32_e32 v118, v0
	v_mov_b32_e32 v119, v0
	v_mov_b32_e32 v120, v0
	v_mov_b32_e32 v121, v0
	v_mov_b32_e32 v90, v0
	v_mov_b32_e32 v91, v0
	v_mov_b32_e32 v92, v0
	v_mov_b32_e32 v93, v0
	v_mov_b32_e32 v122, v0
	v_mov_b32_e32 v123, v0
	v_mov_b32_e32 v124, v0
	v_mov_b32_e32 v125, v0
	v_mov_b32_e32 v94, v0
	v_mov_b32_e32 v95, v0
	v_mov_b32_e32 v96, v0
	v_mov_b32_e32 v97, v0
	v_mov_b32_e32 v126, v0
	v_mov_b32_e32 v127, v0
	v_mov_b32_e32 v128, v0
	v_mov_b32_e32 v129, v0
	v_add_u32_e32 v204, 0x10000, v207
	v_add_u32_e32 v205, 0x14000, v207
	v_add_u32_e32 v210, 0x18000, v207
	v_add_u32_e32 v211, 0x1c000, v207
	s_add_u32 s12, s10, 0x100
	s_addc_u32 s13, s11, 0
	s_cmpk_eq_i32 s42, 0x52
	s_cselect_b32 s17, s1, s13
	s_cselect_b32 s16, s0, s12
	s_cselect_b32 s15, s9, s41
	s_cselect_b32 s14, s8, s40
.LBB0_32:
	ds_read_b128 v[130:133], v204
	ds_read_b128 v[134:137], v204 offset:1024
	ds_read_b128 v[138:141], v204 offset:2048
	ds_read_b128 v[142:145], v204 offset:3072
	ds_read_b128 v[146:149], v205
	ds_read_b128 v[150:153], v205 offset:1024
	ds_read_b128 v[154:157], v205 offset:2048
	ds_read_b128 v[158:161], v205 offset:3072
	ds_read_b128 v[162:165], v208
	ds_read_b128 v[166:169], v208 offset:1024
	ds_read_b128 v[170:173], v208 offset:2048
	ds_read_b128 v[184:187], v208 offset:3072
	ds_read_b128 v[188:191], v208 offset:4096
	s_add_i32 m0, s23, 0xc000
	ds_read_b128 v[192:195], v208 offset:5120
	global_load_lds_dwordx4 v180, s[10:11]
	s_add_i32 m0, s23, 0xe000
	ds_read_b128 v[196:199], v208 offset:6144
	global_load_lds_dwordx4 v182, s[10:11]
	ds_read_b128 v[200:203], v208 offset:7168
	s_waitcnt vmcnt(8) lgkmcnt(0)
	s_barrier
	v_mfma_f32_16x16x32_bf16 v[126:129], v[130:133], v[162:165], v[126:129]
	v_mfma_f32_16x16x32_bf16 v[94:97], v[138:141], v[162:165], v[94:97]
	v_mfma_f32_16x16x32_bf16 v[122:125], v[130:133], v[170:173], v[122:125]
	v_mfma_f32_16x16x32_bf16 v[90:93], v[138:141], v[170:173], v[90:93]
	v_mfma_f32_16x16x32_bf16 v[118:121], v[130:133], v[188:191], v[118:121]
	v_mfma_f32_16x16x32_bf16 v[86:89], v[138:141], v[188:191], v[86:89]
	v_mfma_f32_16x16x32_bf16 v[114:117], v[130:133], v[196:199], v[114:117]
	v_mfma_f32_16x16x32_bf16 v[82:85], v[138:141], v[196:199], v[82:85]
	v_mfma_f32_16x16x32_bf16 v[126:129], v[134:137], v[166:169], v[126:129]
	v_mfma_f32_16x16x32_bf16 v[94:97], v[142:145], v[166:169], v[94:97]
	v_mfma_f32_16x16x32_bf16 v[122:125], v[134:137], v[184:187], v[122:125]
	v_mfma_f32_16x16x32_bf16 v[90:93], v[142:145], v[184:187], v[90:93]
	v_mfma_f32_16x16x32_bf16 v[118:121], v[134:137], v[192:195], v[118:121]
	v_mfma_f32_16x16x32_bf16 v[86:89], v[142:145], v[192:195], v[86:89]
	v_mfma_f32_16x16x32_bf16 v[114:117], v[134:137], v[200:203], v[114:117]
	v_mfma_f32_16x16x32_bf16 v[82:85], v[142:145], v[200:203], v[82:85]
	v_mfma_f32_16x16x32_bf16 v[66:69], v[146:149], v[162:165], v[66:69]
	v_mfma_f32_16x16x32_bf16 v[42:45], v[154:157], v[162:165], v[42:45]
	v_mfma_f32_16x16x32_bf16 v[58:61], v[146:149], v[170:173], v[58:61]
	v_mfma_f32_16x16x32_bf16 v[30:33], v[154:157], v[170:173], v[30:33]
	v_mfma_f32_16x16x32_bf16 v[54:57], v[146:149], v[188:191], v[54:57]
	v_mfma_f32_16x16x32_bf16 v[22:25], v[154:157], v[188:191], v[22:25]
	v_mfma_f32_16x16x32_bf16 v[50:53], v[146:149], v[196:199], v[50:53]
	v_mfma_f32_16x16x32_bf16 v[18:21], v[154:157], v[196:199], v[18:21]
	v_mfma_f32_16x16x32_bf16 v[66:69], v[150:153], v[166:169], v[66:69]
	v_mfma_f32_16x16x32_bf16 v[42:45], v[158:161], v[166:169], v[42:45]
	v_mfma_f32_16x16x32_bf16 v[58:61], v[150:153], v[184:187], v[58:61]
	v_mfma_f32_16x16x32_bf16 v[30:33], v[158:161], v[184:187], v[30:33]
	v_mfma_f32_16x16x32_bf16 v[54:57], v[150:153], v[192:195], v[54:57]
	v_mfma_f32_16x16x32_bf16 v[22:25], v[158:161], v[192:195], v[22:25]
	v_mfma_f32_16x16x32_bf16 v[50:53], v[150:153], v[200:203], v[50:53]
	v_mfma_f32_16x16x32_bf16 v[18:21], v[158:161], v[200:203], v[18:21]
	s_barrier
	ds_read_b128 v[162:165], v208 offset:16384
	s_add_i32 m0, s22, 0x10000
	ds_read_b128 v[166:169], v208 offset:17408
	global_load_lds_dwordx4 v178, s[14:15]
	s_add_i32 m0, s22, 0x12000
	s_add_u32 s10, s14, 0x158000
	s_addc_u32 s11, s15, 0
	ds_read_b128 v[170:173], v208 offset:18432
	global_load_lds_dwordx4 v176, s[14:15]
	s_add_i32 m0, s22, 0x14000
	ds_read_b128 v[184:187], v208 offset:19456
	global_load_lds_dwordx4 v178, s[10:11]
	s_add_i32 m0, s22, 0x16000
	ds_read_b128 v[188:191], v208 offset:20480
	global_load_lds_dwordx4 v176, s[10:11]
	s_mov_b32 m0, s23
	ds_read_b128 v[192:195], v208 offset:21504
	global_load_lds_dwordx4 v178, s[16:17]
	s_mov_b32 m0, s24
	ds_read_b128 v[196:199], v208 offset:22528
	global_load_lds_dwordx4 v176, s[16:17]
	ds_read_b128 v[200:203], v208 offset:23552
	s_waitcnt vmcnt(8) lgkmcnt(0)
	s_barrier
	v_mfma_f32_16x16x32_bf16 v[110:113], v[130:133], v[162:165], v[110:113]
	v_mfma_f32_16x16x32_bf16 v[78:81], v[138:141], v[162:165], v[78:81]
	v_mfma_f32_16x16x32_bf16 v[106:109], v[130:133], v[170:173], v[106:109]
	v_mfma_f32_16x16x32_bf16 v[74:77], v[138:141], v[170:173], v[74:77]
	v_mfma_f32_16x16x32_bf16 v[102:105], v[130:133], v[188:191], v[102:105]
	v_mfma_f32_16x16x32_bf16 v[70:73], v[138:141], v[188:191], v[70:73]
	v_mfma_f32_16x16x32_bf16 v[98:101], v[130:133], v[196:199], v[98:101]
	v_mfma_f32_16x16x32_bf16 v[62:65], v[138:141], v[196:199], v[62:65]
	v_mfma_f32_16x16x32_bf16 v[110:113], v[134:137], v[166:169], v[110:113]
	v_mfma_f32_16x16x32_bf16 v[78:81], v[142:145], v[166:169], v[78:81]
	v_mfma_f32_16x16x32_bf16 v[106:109], v[134:137], v[184:187], v[106:109]
	v_mfma_f32_16x16x32_bf16 v[74:77], v[142:145], v[184:187], v[74:77]
	v_mfma_f32_16x16x32_bf16 v[102:105], v[134:137], v[192:195], v[102:105]
	v_mfma_f32_16x16x32_bf16 v[70:73], v[142:145], v[192:195], v[70:73]
	v_mfma_f32_16x16x32_bf16 v[98:101], v[134:137], v[200:203], v[98:101]
	v_mfma_f32_16x16x32_bf16 v[62:65], v[142:145], v[200:203], v[62:65]
	v_mfma_f32_16x16x32_bf16 v[46:49], v[146:149], v[162:165], v[46:49]
	v_mfma_f32_16x16x32_bf16 v[12:15], v[154:157], v[162:165], v[12:15]
	v_mfma_f32_16x16x32_bf16 v[38:41], v[146:149], v[170:173], v[38:41]
	v_mfma_f32_16x16x32_bf16 v[8:11], v[154:157], v[170:173], v[8:11]
	v_mfma_f32_16x16x32_bf16 v[34:37], v[146:149], v[188:191], v[34:37]
	v_mfma_f32_16x16x32_bf16 v[4:7], v[154:157], v[188:191], v[4:7]
	v_mfma_f32_16x16x32_bf16 v[26:29], v[146:149], v[196:199], v[26:29]
	v_mfma_f32_16x16x32_bf16 v[0:3], v[154:157], v[196:199], v[0:3]
	v_mfma_f32_16x16x32_bf16 v[46:49], v[150:153], v[166:169], v[46:49]
	v_mfma_f32_16x16x32_bf16 v[12:15], v[158:161], v[166:169], v[12:15]
	v_mfma_f32_16x16x32_bf16 v[38:41], v[150:153], v[184:187], v[38:41]
	v_mfma_f32_16x16x32_bf16 v[8:11], v[158:161], v[184:187], v[8:11]
	v_mfma_f32_16x16x32_bf16 v[34:37], v[150:153], v[192:195], v[34:37]
	v_mfma_f32_16x16x32_bf16 v[4:7], v[158:161], v[192:195], v[4:7]
	v_mfma_f32_16x16x32_bf16 v[26:29], v[150:153], v[200:203], v[26:29]
	v_mfma_f32_16x16x32_bf16 v[0:3], v[158:161], v[200:203], v[0:3]
	s_barrier
	s_add_u32 s100, s16, 0x158000
	s_addc_u32 s101, s17, 0
	ds_read_b128 v[130:133], v210
	ds_read_b128 v[134:137], v210 offset:1024
	ds_read_b128 v[138:141], v210 offset:2048
	ds_read_b128 v[142:145], v210 offset:3072
	ds_read_b128 v[146:149], v211
	ds_read_b128 v[150:153], v211 offset:1024
	ds_read_b128 v[154:157], v211 offset:2048
	ds_read_b128 v[158:161], v211 offset:3072
	ds_read_b128 v[162:165], v208 offset:32768
	ds_read_b128 v[166:169], v208 offset:33792
	ds_read_b128 v[170:173], v208 offset:34816
	ds_read_b128 v[184:187], v208 offset:35840
	ds_read_b128 v[188:191], v208 offset:36864
	s_mov_b32 m0, s25
	ds_read_b128 v[192:195], v208 offset:37888
	global_load_lds_dwordx4 v178, s[100:101]
	s_mov_b32 m0, s26
	ds_read_b128 v[196:199], v208 offset:38912
	global_load_lds_dwordx4 v176, s[100:101]
	ds_read_b128 v[200:203], v208 offset:39936
	s_waitcnt vmcnt(8) lgkmcnt(0)
	s_barrier
	v_mfma_f32_16x16x32_bf16 v[126:129], v[130:133], v[162:165], v[126:129]
	v_mfma_f32_16x16x32_bf16 v[94:97], v[138:141], v[162:165], v[94:97]
	v_mfma_f32_16x16x32_bf16 v[122:125], v[130:133], v[170:173], v[122:125]
	v_mfma_f32_16x16x32_bf16 v[90:93], v[138:141], v[170:173], v[90:93]
	v_mfma_f32_16x16x32_bf16 v[118:121], v[130:133], v[188:191], v[118:121]
	v_mfma_f32_16x16x32_bf16 v[86:89], v[138:141], v[188:191], v[86:89]
	v_mfma_f32_16x16x32_bf16 v[114:117], v[130:133], v[196:199], v[114:117]
	v_mfma_f32_16x16x32_bf16 v[82:85], v[138:141], v[196:199], v[82:85]
	v_mfma_f32_16x16x32_bf16 v[126:129], v[134:137], v[166:169], v[126:129]
	v_mfma_f32_16x16x32_bf16 v[94:97], v[142:145], v[166:169], v[94:97]
	v_mfma_f32_16x16x32_bf16 v[122:125], v[134:137], v[184:187], v[122:125]
	v_mfma_f32_16x16x32_bf16 v[90:93], v[142:145], v[184:187], v[90:93]
	v_mfma_f32_16x16x32_bf16 v[118:121], v[134:137], v[192:195], v[118:121]
	v_mfma_f32_16x16x32_bf16 v[86:89], v[142:145], v[192:195], v[86:89]
	v_mfma_f32_16x16x32_bf16 v[114:117], v[134:137], v[200:203], v[114:117]
	v_mfma_f32_16x16x32_bf16 v[82:85], v[142:145], v[200:203], v[82:85]
	v_mfma_f32_16x16x32_bf16 v[66:69], v[146:149], v[162:165], v[66:69]
	v_mfma_f32_16x16x32_bf16 v[42:45], v[154:157], v[162:165], v[42:45]
	v_mfma_f32_16x16x32_bf16 v[58:61], v[146:149], v[170:173], v[58:61]
	v_mfma_f32_16x16x32_bf16 v[30:33], v[154:157], v[170:173], v[30:33]
	v_mfma_f32_16x16x32_bf16 v[54:57], v[146:149], v[188:191], v[54:57]
	v_mfma_f32_16x16x32_bf16 v[22:25], v[154:157], v[188:191], v[22:25]
	v_mfma_f32_16x16x32_bf16 v[50:53], v[146:149], v[196:199], v[50:53]
	v_mfma_f32_16x16x32_bf16 v[18:21], v[154:157], v[196:199], v[18:21]
	v_mfma_f32_16x16x32_bf16 v[66:69], v[150:153], v[166:169], v[66:69]
	v_mfma_f32_16x16x32_bf16 v[42:45], v[158:161], v[166:169], v[42:45]
	v_mfma_f32_16x16x32_bf16 v[58:61], v[150:153], v[184:187], v[58:61]
	v_mfma_f32_16x16x32_bf16 v[30:33], v[158:161], v[184:187], v[30:33]
	v_mfma_f32_16x16x32_bf16 v[54:57], v[150:153], v[192:195], v[54:57]
	v_mfma_f32_16x16x32_bf16 v[22:25], v[158:161], v[192:195], v[22:25]
	v_mfma_f32_16x16x32_bf16 v[50:53], v[150:153], v[200:203], v[50:53]
	v_mfma_f32_16x16x32_bf16 v[18:21], v[158:161], v[200:203], v[18:21]
	s_barrier
	ds_read_b128 v[162:165], v208 offset:49152
	s_add_i32 m0, s22, 0x17f80
	ds_read_b128 v[166:169], v208 offset:50176
	global_load_lds_dwordx4 v178, s[14:15] offset:128
	s_add_i32 m0, s22, 0x19f80
	ds_read_b128 v[170:173], v208 offset:51200
	global_load_lds_dwordx4 v176, s[14:15] offset:128
	s_add_i32 m0, s22, 0x1bf80
	ds_read_b128 v[184:187], v208 offset:52224
	global_load_lds_dwordx4 v178, s[10:11] offset:128
	s_add_i32 m0, s22, 0x1df80
	ds_read_b128 v[188:191], v208 offset:53248
	global_load_lds_dwordx4 v176, s[10:11] offset:128
	s_add_i32 m0, s31, 0xffffff80
	ds_read_b128 v[192:195], v208 offset:54272
	global_load_lds_dwordx4 v178, s[16:17] offset:128
	s_add_i32 m0, s34, 0xffffff80
	ds_read_b128 v[196:199], v208 offset:55296
	global_load_lds_dwordx4 v176, s[16:17] offset:128
	ds_read_b128 v[200:203], v208 offset:56320
	s_add_i32 s42, s42, 2
	s_add_u32 s40, s40, 0x100
	s_addc_u32 s41, s41, 0
	s_mov_b64 s[10:11], s[12:13]
	s_add_u32 s12, s10, 0x100
	s_addc_u32 s13, s11, 0
	s_cmpk_eq_i32 s42, 0x52
	s_cselect_b32 s17, s1, s13
	s_cselect_b32 s16, s0, s12
	s_cselect_b32 s15, s9, s41
	s_cselect_b32 s14, s8, s40
	s_cmpk_gt_u32 s42, 0x53
	s_waitcnt vmcnt(8) lgkmcnt(0)
	s_barrier
	v_mfma_f32_16x16x32_bf16 v[110:113], v[130:133], v[162:165], v[110:113]
	v_mfma_f32_16x16x32_bf16 v[78:81], v[138:141], v[162:165], v[78:81]
	v_mfma_f32_16x16x32_bf16 v[106:109], v[130:133], v[170:173], v[106:109]
	v_mfma_f32_16x16x32_bf16 v[74:77], v[138:141], v[170:173], v[74:77]
	v_mfma_f32_16x16x32_bf16 v[102:105], v[130:133], v[188:191], v[102:105]
	v_mfma_f32_16x16x32_bf16 v[70:73], v[138:141], v[188:191], v[70:73]
	v_mfma_f32_16x16x32_bf16 v[98:101], v[130:133], v[196:199], v[98:101]
	v_mfma_f32_16x16x32_bf16 v[62:65], v[138:141], v[196:199], v[62:65]
	v_mfma_f32_16x16x32_bf16 v[110:113], v[134:137], v[166:169], v[110:113]
	v_mfma_f32_16x16x32_bf16 v[78:81], v[142:145], v[166:169], v[78:81]
	v_mfma_f32_16x16x32_bf16 v[106:109], v[134:137], v[184:187], v[106:109]
	v_mfma_f32_16x16x32_bf16 v[74:77], v[142:145], v[184:187], v[74:77]
	v_mfma_f32_16x16x32_bf16 v[102:105], v[134:137], v[192:195], v[102:105]
	v_mfma_f32_16x16x32_bf16 v[70:73], v[142:145], v[192:195], v[70:73]
	v_mfma_f32_16x16x32_bf16 v[98:101], v[134:137], v[200:203], v[98:101]
	v_mfma_f32_16x16x32_bf16 v[62:65], v[142:145], v[200:203], v[62:65]
	v_mfma_f32_16x16x32_bf16 v[46:49], v[146:149], v[162:165], v[46:49]
	v_mfma_f32_16x16x32_bf16 v[12:15], v[154:157], v[162:165], v[12:15]
	v_mfma_f32_16x16x32_bf16 v[38:41], v[146:149], v[170:173], v[38:41]
	v_mfma_f32_16x16x32_bf16 v[8:11], v[154:157], v[170:173], v[8:11]
	v_mfma_f32_16x16x32_bf16 v[34:37], v[146:149], v[188:191], v[34:37]
	v_mfma_f32_16x16x32_bf16 v[4:7], v[154:157], v[188:191], v[4:7]
	v_mfma_f32_16x16x32_bf16 v[26:29], v[146:149], v[196:199], v[26:29]
	v_mfma_f32_16x16x32_bf16 v[0:3], v[154:157], v[196:199], v[0:3]
	v_mfma_f32_16x16x32_bf16 v[46:49], v[150:153], v[166:169], v[46:49]
	v_mfma_f32_16x16x32_bf16 v[12:15], v[158:161], v[166:169], v[12:15]
	v_mfma_f32_16x16x32_bf16 v[38:41], v[150:153], v[184:187], v[38:41]
	v_mfma_f32_16x16x32_bf16 v[8:11], v[158:161], v[184:187], v[8:11]
	v_mfma_f32_16x16x32_bf16 v[34:37], v[150:153], v[192:195], v[34:37]
	v_mfma_f32_16x16x32_bf16 v[4:7], v[158:161], v[192:195], v[4:7]
	v_mfma_f32_16x16x32_bf16 v[26:29], v[150:153], v[200:203], v[26:29]
	v_mfma_f32_16x16x32_bf16 v[0:3], v[158:161], v[200:203], v[0:3]
	s_barrier
	s_cbranch_scc0 .LBB0_32
	s_and_b64 vcc, exec, s[6:7]
	s_cbranch_vccz .LBB0_35
	s_barrier

.LBB0_67:
	s_ashr_i32 s21, s20, 31
	s_lshl_b64 s[10:11], s[20:21], 20
	s_add_u32 s22, s34, s10
	s_addc_u32 s23, s35, s11
	s_and_b64 s[10:11], s[4:5], exec
	s_cselect_b32 s21, s23, s7
	s_cselect_b32 s28, s22, s6
	s_ashr_i32 s19, s18, 31
	s_lshl_b64 s[10:11], s[18:19], 20
	s_add_u32 s24, s36, s10
	s_addc_u32 s25, s37, s11
	s_and_b64 s[10:11], s[4:5], exec
	s_cselect_b32 s19, s25, s9
	s_cselect_b32 s29, s24, s8
	s_add_u32 s6, s6, 0x80080
	s_addc_u32 s7, s7, 0
	s_add_u32 s30, s8, 0x100
	v_mov_b32_e32 v4, 0
	s_addc_u32 s31, s9, 0
	s_mov_b32 s51, -2
	v_mov_b32_e32 v5, v4
	v_mov_b32_e32 v6, v4
	v_mov_b32_e32 v7, v4
	v_mov_b32_e32 v0, v4
	v_mov_b32_e32 v1, v4
	v_mov_b32_e32 v2, v4
	v_mov_b32_e32 v3, v4
	v_mov_b32_e32 v26, v4
	v_mov_b32_e32 v27, v4
	v_mov_b32_e32 v28, v4
	v_mov_b32_e32 v29, v4
	v_mov_b32_e32 v34, v4
	v_mov_b32_e32 v35, v4
	v_mov_b32_e32 v36, v4
	v_mov_b32_e32 v37, v4
	v_mov_b32_e32 v42, v4
	v_mov_b32_e32 v43, v4
	v_mov_b32_e32 v44, v4
	v_mov_b32_e32 v45, v4
	v_mov_b32_e32 v50, v4
	v_mov_b32_e32 v51, v4
	v_mov_b32_e32 v52, v4
	v_mov_b32_e32 v53, v4
	v_mov_b32_e32 v90, v4
	v_mov_b32_e32 v91, v4
	v_mov_b32_e32 v92, v4
	v_mov_b32_e32 v93, v4
	v_mov_b32_e32 v94, v4
	v_mov_b32_e32 v95, v4
	v_mov_b32_e32 v96, v4
	v_mov_b32_e32 v97, v4
	v_mov_b32_e32 v12, v4
	v_mov_b32_e32 v13, v4
	v_mov_b32_e32 v14, v4
	v_mov_b32_e32 v15, v4
	v_mov_b32_e32 v8, v4
	v_mov_b32_e32 v9, v4
	v_mov_b32_e32 v10, v4
	v_mov_b32_e32 v11, v4
	v_mov_b32_e32 v18, v4
	v_mov_b32_e32 v19, v4
	v_mov_b32_e32 v20, v4
	v_mov_b32_e32 v21, v4
	v_mov_b32_e32 v22, v4
	v_mov_b32_e32 v23, v4
	v_mov_b32_e32 v24, v4
	v_mov_b32_e32 v25, v4
	v_mov_b32_e32 v30, v4
	v_mov_b32_e32 v31, v4
	v_mov_b32_e32 v32, v4
	v_mov_b32_e32 v33, v4
	v_mov_b32_e32 v38, v4
	v_mov_b32_e32 v39, v4
	v_mov_b32_e32 v40, v4
	v_mov_b32_e32 v41, v4
	v_mov_b32_e32 v46, v4
	v_mov_b32_e32 v47, v4
	v_mov_b32_e32 v48, v4
	v_mov_b32_e32 v49, v4
	s_waitcnt vmcnt(0)
	v_mov_b32_e32 v58, v4
	v_mov_b32_e32 v59, v4
	v_mov_b32_e32 v60, v4
	v_mov_b32_e32 v61, v4
	v_mov_b32_e32 v98, v4
	v_mov_b32_e32 v99, v4
	v_mov_b32_e32 v100, v4
	v_mov_b32_e32 v101, v4
	v_mov_b32_e32 v102, v4
	v_mov_b32_e32 v103, v4
	v_mov_b32_e32 v104, v4
	v_mov_b32_e32 v105, v4
	v_mov_b32_e32 v122, v4
	v_mov_b32_e32 v123, v4
	v_mov_b32_e32 v124, v4
	v_mov_b32_e32 v125, v4
	v_mov_b32_e32 v130, v4
	v_mov_b32_e32 v131, v4
	v_mov_b32_e32 v132, v4
	v_mov_b32_e32 v133, v4
	v_mov_b32_e32 v138, v4
	v_mov_b32_e32 v139, v4
	v_mov_b32_e32 v140, v4
	v_mov_b32_e32 v141, v4
	v_mov_b32_e32 v146, v4
	v_mov_b32_e32 v147, v4
	v_mov_b32_e32 v148, v4
	v_mov_b32_e32 v149, v4
	v_mov_b32_e32 v154, v4
	v_mov_b32_e32 v155, v4
	v_mov_b32_e32 v156, v4
	v_mov_b32_e32 v157, v4
	v_mov_b32_e32 v158, v4
	v_mov_b32_e32 v159, v4
	v_mov_b32_e32 v160, v4
	v_mov_b32_e32 v161, v4
	v_mov_b32_e32 v106, v4
	v_mov_b32_e32 v107, v4
	v_mov_b32_e32 v108, v4
	v_mov_b32_e32 v109, v4
	v_mov_b32_e32 v110, v4
	v_mov_b32_e32 v111, v4
	v_mov_b32_e32 v112, v4
	v_mov_b32_e32 v113, v4
	v_mov_b32_e32 v114, v4
	v_mov_b32_e32 v115, v4
	v_mov_b32_e32 v116, v4
	v_mov_b32_e32 v117, v4
	v_mov_b32_e32 v118, v4
	v_mov_b32_e32 v119, v4
	v_mov_b32_e32 v120, v4
	v_mov_b32_e32 v121, v4
	v_mov_b32_e32 v126, v4
	v_mov_b32_e32 v127, v4
	v_mov_b32_e32 v128, v4
	v_mov_b32_e32 v129, v4
	v_mov_b32_e32 v134, v4
	v_mov_b32_e32 v135, v4
	v_mov_b32_e32 v136, v4
	v_mov_b32_e32 v137, v4
	v_mov_b32_e32 v142, v4
	v_mov_b32_e32 v143, v4
	v_mov_b32_e32 v144, v4
	v_mov_b32_e32 v145, v4
	v_mov_b32_e32 v150, v4
	v_mov_b32_e32 v151, v4
	v_mov_b32_e32 v152, v4
	v_mov_b32_e32 v153, v4
	v_add_u32_e32 v214, 0x10000, v190
	v_add_u32_e32 v215, 0x14000, v190
	v_add_u32_e32 v234, 0x18000, v190
	v_add_u32_e32 v235, 0x1c000, v190
	s_add_u32 s8, s6, 0xfff80080
	s_addc_u32 s9, s7, -1
	s_cmp_eq_u32 s51, 28
	s_cselect_b32 s11, s21, s9
	s_cselect_b32 s10, s28, s8
	s_cselect_b32 s9, s19, s31
	s_cselect_b32 s8, s29, s30
.LBB0_68:
	ds_read_b128 v[54:57], v214
	ds_read_b128 v[62:65], v214 offset:1024
	ds_read_b128 v[66:69], v214 offset:2048
	ds_read_b128 v[70:73], v214 offset:3072
	ds_read_b128 v[74:77], v215
	ds_read_b128 v[78:81], v215 offset:1024
	ds_read_b128 v[82:85], v215 offset:2048
	ds_read_b128 v[86:89], v215 offset:3072
	ds_read_b128 v[170:173], v192
	ds_read_b128 v[184:187], v192 offset:1024
	ds_read_b128 v[194:197], v192 offset:2048
	ds_read_b128 v[198:201], v192 offset:3072
	ds_read_b128 v[202:205], v192 offset:4096
	s_add_i32 m0, s41, 0xc000
	ds_read_b128 v[206:209], v192 offset:5120
	global_load_lds_dwordx4 v180, s[6:7]
	s_add_i32 m0, s41, 0xe000
	ds_read_b128 v[210:213], v192 offset:6144
	global_load_lds_dwordx4 v182, s[6:7]
	ds_read_b128 v[222:225], v192 offset:7168
	s_waitcnt vmcnt(8) lgkmcnt(0)
	s_barrier
	v_mfma_f32_16x16x32_bf16 v[150:153], v[54:57], v[170:173], v[150:153]
	v_mfma_f32_16x16x32_bf16 v[142:145], v[66:69], v[170:173], v[142:145]
	v_mfma_f32_16x16x32_bf16 v[134:137], v[54:57], v[194:197], v[134:137]
	v_mfma_f32_16x16x32_bf16 v[126:129], v[66:69], v[194:197], v[126:129]
	v_mfma_f32_16x16x32_bf16 v[118:121], v[54:57], v[202:205], v[118:121]
	v_mfma_f32_16x16x32_bf16 v[114:117], v[66:69], v[202:205], v[114:117]
	v_mfma_f32_16x16x32_bf16 v[110:113], v[54:57], v[210:213], v[110:113]
	v_mfma_f32_16x16x32_bf16 v[106:109], v[66:69], v[210:213], v[106:109]
	v_mfma_f32_16x16x32_bf16 v[150:153], v[62:65], v[184:187], v[150:153]
	v_mfma_f32_16x16x32_bf16 v[142:145], v[70:73], v[184:187], v[142:145]
	v_mfma_f32_16x16x32_bf16 v[134:137], v[62:65], v[198:201], v[134:137]
	v_mfma_f32_16x16x32_bf16 v[126:129], v[70:73], v[198:201], v[126:129]
	v_mfma_f32_16x16x32_bf16 v[118:121], v[62:65], v[206:209], v[118:121]
	v_mfma_f32_16x16x32_bf16 v[114:117], v[70:73], v[206:209], v[114:117]
	v_mfma_f32_16x16x32_bf16 v[110:113], v[62:65], v[222:225], v[110:113]
	v_mfma_f32_16x16x32_bf16 v[106:109], v[70:73], v[222:225], v[106:109]
	v_mfma_f32_16x16x32_bf16 v[158:161], v[74:77], v[170:173], v[158:161]
	v_mfma_f32_16x16x32_bf16 v[154:157], v[82:85], v[170:173], v[154:157]
	v_mfma_f32_16x16x32_bf16 v[146:149], v[74:77], v[194:197], v[146:149]
	v_mfma_f32_16x16x32_bf16 v[138:141], v[82:85], v[194:197], v[138:141]
	v_mfma_f32_16x16x32_bf16 v[130:133], v[74:77], v[202:205], v[130:133]
	v_mfma_f32_16x16x32_bf16 v[122:125], v[82:85], v[202:205], v[122:125]
	v_mfma_f32_16x16x32_bf16 v[102:105], v[74:77], v[210:213], v[102:105]
	v_mfma_f32_16x16x32_bf16 v[98:101], v[82:85], v[210:213], v[98:101]
	v_mfma_f32_16x16x32_bf16 v[158:161], v[78:81], v[184:187], v[158:161]
	v_mfma_f32_16x16x32_bf16 v[154:157], v[86:89], v[184:187], v[154:157]
	v_mfma_f32_16x16x32_bf16 v[146:149], v[78:81], v[198:201], v[146:149]
	v_mfma_f32_16x16x32_bf16 v[138:141], v[86:89], v[198:201], v[138:141]
	v_mfma_f32_16x16x32_bf16 v[130:133], v[78:81], v[206:209], v[130:133]
	v_mfma_f32_16x16x32_bf16 v[122:125], v[86:89], v[206:209], v[122:125]
	v_mfma_f32_16x16x32_bf16 v[102:105], v[78:81], v[222:225], v[102:105]
	v_mfma_f32_16x16x32_bf16 v[98:101], v[86:89], v[222:225], v[98:101]
	s_barrier
	ds_read_b128 v[170:173], v192 offset:16384
	s_add_i32 m0, s38, 0x10000
	ds_read_b128 v[184:187], v192 offset:17408
	global_load_lds_dwordx4 v166, s[8:9]
	s_add_i32 m0, s38, 0x12000
	s_add_u32 s52, s8, 0x80000
	s_addc_u32 s53, s9, 0
	ds_read_b128 v[194:197], v192 offset:18432
	global_load_lds_dwordx4 v162, s[8:9]
	s_add_i32 m0, s38, 0x14000
	ds_read_b128 v[198:201], v192 offset:19456
	global_load_lds_dwordx4 v166, s[52:53]
	s_add_i32 m0, s38, 0x16000
	ds_read_b128 v[202:205], v192 offset:20480
	global_load_lds_dwordx4 v162, s[52:53]
	s_mov_b32 m0, s41
	ds_read_b128 v[206:209], v192 offset:21504
	global_load_lds_dwordx4 v168, s[10:11]
	s_mov_b32 m0, s42
	ds_read_b128 v[210:213], v192 offset:22528
	global_load_lds_dwordx4 v164, s[10:11]
	ds_read_b128 v[222:225], v192 offset:23552
	s_waitcnt vmcnt(8) lgkmcnt(0)
	s_barrier
	v_mfma_f32_16x16x32_bf16 v[58:61], v[54:57], v[170:173], v[58:61]
	v_mfma_f32_16x16x32_bf16 v[46:49], v[66:69], v[170:173], v[46:49]
	v_mfma_f32_16x16x32_bf16 v[38:41], v[54:57], v[194:197], v[38:41]
	v_mfma_f32_16x16x32_bf16 v[30:33], v[66:69], v[194:197], v[30:33]
	v_mfma_f32_16x16x32_bf16 v[22:25], v[54:57], v[202:205], v[22:25]
	v_mfma_f32_16x16x32_bf16 v[18:21], v[66:69], v[202:205], v[18:21]
	v_mfma_f32_16x16x32_bf16 v[8:11], v[54:57], v[210:213], v[8:11]
	v_mfma_f32_16x16x32_bf16 v[12:15], v[66:69], v[210:213], v[12:15]
	v_mfma_f32_16x16x32_bf16 v[58:61], v[62:65], v[184:187], v[58:61]
	v_mfma_f32_16x16x32_bf16 v[46:49], v[70:73], v[184:187], v[46:49]
	v_mfma_f32_16x16x32_bf16 v[38:41], v[62:65], v[198:201], v[38:41]
	v_mfma_f32_16x16x32_bf16 v[30:33], v[70:73], v[198:201], v[30:33]
	v_mfma_f32_16x16x32_bf16 v[22:25], v[62:65], v[206:209], v[22:25]
	v_mfma_f32_16x16x32_bf16 v[18:21], v[70:73], v[206:209], v[18:21]
	v_mfma_f32_16x16x32_bf16 v[8:11], v[62:65], v[222:225], v[8:11]
	v_mfma_f32_16x16x32_bf16 v[12:15], v[70:73], v[222:225], v[12:15]
	v_mfma_f32_16x16x32_bf16 v[50:53], v[74:77], v[194:197], v[50:53]
	v_mfma_f32_16x16x32_bf16 v[42:45], v[82:85], v[194:197], v[42:45]
	v_mfma_f32_16x16x32_bf16 v[34:37], v[74:77], v[202:205], v[34:37]
	v_mfma_f32_16x16x32_bf16 v[26:29], v[82:85], v[202:205], v[26:29]
	v_mfma_f32_16x16x32_bf16 v[0:3], v[74:77], v[210:213], v[0:3]
	v_mfma_f32_16x16x32_bf16 v[4:7], v[82:85], v[210:213], v[4:7]
	v_mfma_f32_16x16x32_bf16 v[54:57], v[74:77], v[170:173], v[94:97]
	v_mfma_f32_16x16x32_bf16 v[62:65], v[82:85], v[170:173], v[90:93]
	v_mfma_f32_16x16x32_bf16 v[50:53], v[78:81], v[198:201], v[50:53]
	v_mfma_f32_16x16x32_bf16 v[42:45], v[86:89], v[198:201], v[42:45]
	v_mfma_f32_16x16x32_bf16 v[34:37], v[78:81], v[206:209], v[34:37]
	v_mfma_f32_16x16x32_bf16 v[26:29], v[86:89], v[206:209], v[26:29]
	v_mfma_f32_16x16x32_bf16 v[0:3], v[78:81], v[222:225], v[0:3]
	v_mfma_f32_16x16x32_bf16 v[4:7], v[86:89], v[222:225], v[4:7]
	v_mfma_f32_16x16x32_bf16 v[54:57], v[78:81], v[184:187], v[54:57]
	v_mfma_f32_16x16x32_bf16 v[62:65], v[86:89], v[184:187], v[62:65]
	s_barrier
	s_add_u32 s100, s10, 0x80000
	s_addc_u32 s101, s11, 0
	ds_read_b128 v[66:69], v234
	ds_read_b128 v[70:73], v234 offset:1024
	ds_read_b128 v[74:77], v234 offset:2048
	ds_read_b128 v[78:81], v234 offset:3072
	ds_read_b128 v[82:85], v235
	ds_read_b128 v[86:89], v235 offset:1024
	ds_read_b128 v[170:173], v235 offset:2048
	ds_read_b128 v[184:187], v235 offset:3072
	ds_read_b128 v[90:93], v192 offset:32768
	ds_read_b128 v[94:97], v192 offset:33792
	ds_read_b128 v[194:197], v192 offset:34816
	ds_read_b128 v[198:201], v192 offset:35840
	ds_read_b128 v[202:205], v192 offset:36864
	s_mov_b32 m0, s43
	ds_read_b128 v[206:209], v192 offset:37888
	global_load_lds_dwordx4 v168, s[100:101]
	s_mov_b32 m0, s44
	ds_read_b128 v[210:213], v192 offset:38912
	global_load_lds_dwordx4 v164, s[100:101]
	ds_read_b128 v[222:225], v192 offset:39936
	s_waitcnt vmcnt(8) lgkmcnt(0)
	s_barrier
	v_mfma_f32_16x16x32_bf16 v[150:153], v[66:69], v[90:93], v[150:153]
	v_mfma_f32_16x16x32_bf16 v[142:145], v[74:77], v[90:93], v[142:145]
	v_mfma_f32_16x16x32_bf16 v[134:137], v[66:69], v[194:197], v[134:137]
	v_mfma_f32_16x16x32_bf16 v[126:129], v[74:77], v[194:197], v[126:129]
	v_mfma_f32_16x16x32_bf16 v[118:121], v[66:69], v[202:205], v[118:121]
	v_mfma_f32_16x16x32_bf16 v[114:117], v[74:77], v[202:205], v[114:117]
	v_mfma_f32_16x16x32_bf16 v[110:113], v[66:69], v[210:213], v[110:113]
	v_mfma_f32_16x16x32_bf16 v[106:109], v[74:77], v[210:213], v[106:109]
	v_mfma_f32_16x16x32_bf16 v[150:153], v[70:73], v[94:97], v[150:153]
	v_mfma_f32_16x16x32_bf16 v[142:145], v[78:81], v[94:97], v[142:145]
	v_mfma_f32_16x16x32_bf16 v[134:137], v[70:73], v[198:201], v[134:137]
	v_mfma_f32_16x16x32_bf16 v[126:129], v[78:81], v[198:201], v[126:129]
	v_mfma_f32_16x16x32_bf16 v[118:121], v[70:73], v[206:209], v[118:121]
	v_mfma_f32_16x16x32_bf16 v[114:117], v[78:81], v[206:209], v[114:117]
	v_mfma_f32_16x16x32_bf16 v[110:113], v[70:73], v[222:225], v[110:113]
	v_mfma_f32_16x16x32_bf16 v[106:109], v[78:81], v[222:225], v[106:109]
	v_mfma_f32_16x16x32_bf16 v[158:161], v[82:85], v[90:93], v[158:161]
	v_mfma_f32_16x16x32_bf16 v[90:93], v[170:173], v[90:93], v[154:157]
	v_mfma_f32_16x16x32_bf16 v[154:157], v[184:187], v[94:97], v[90:93]
	v_mfma_f32_16x16x32_bf16 v[90:93], v[82:85], v[194:197], v[146:149]
	v_mfma_f32_16x16x32_bf16 v[146:149], v[86:89], v[198:201], v[90:93]
	v_mfma_f32_16x16x32_bf16 v[90:93], v[170:173], v[194:197], v[138:141]
	v_mfma_f32_16x16x32_bf16 v[138:141], v[184:187], v[198:201], v[90:93]
	v_mfma_f32_16x16x32_bf16 v[90:93], v[82:85], v[202:205], v[130:133]
	v_mfma_f32_16x16x32_bf16 v[130:133], v[86:89], v[206:209], v[90:93]
	v_mfma_f32_16x16x32_bf16 v[90:93], v[170:173], v[202:205], v[122:125]
	v_mfma_f32_16x16x32_bf16 v[122:125], v[184:187], v[206:209], v[90:93]
	v_mfma_f32_16x16x32_bf16 v[90:93], v[82:85], v[210:213], v[102:105]
	v_mfma_f32_16x16x32_bf16 v[102:105], v[86:89], v[222:225], v[90:93]
	v_mfma_f32_16x16x32_bf16 v[90:93], v[170:173], v[210:213], v[98:101]
	v_mfma_f32_16x16x32_bf16 v[158:161], v[86:89], v[94:97], v[158:161]
	v_mfma_f32_16x16x32_bf16 v[98:101], v[184:187], v[222:225], v[90:93]
	s_barrier
	ds_read_b128 v[90:93], v192 offset:49152
	s_add_i32 m0, s38, 0x17f80
	ds_read_b128 v[194:197], v192 offset:50176
	global_load_lds_dwordx4 v166, s[8:9] offset:128
	s_add_i32 m0, s38, 0x19f80
	ds_read_b128 v[198:201], v192 offset:51200
	global_load_lds_dwordx4 v162, s[8:9] offset:128
	s_add_i32 m0, s38, 0x1bf80
	ds_read_b128 v[202:205], v192 offset:52224
	global_load_lds_dwordx4 v166, s[52:53] offset:128
	s_add_i32 m0, s38, 0x1df80
	ds_read_b128 v[206:209], v192 offset:53248
	global_load_lds_dwordx4 v162, s[52:53] offset:128
	s_add_i32 m0, s46, 0xffffff80
	ds_read_b128 v[210:213], v192 offset:54272
	global_load_lds_dwordx4 v168, s[10:11] offset:128
	s_add_i32 m0, s47, 0xffffff80
	ds_read_b128 v[222:225], v192 offset:55296
	global_load_lds_dwordx4 v164, s[10:11] offset:128
	ds_read_b128 v[230:233], v192 offset:56320
	s_add_i32 s51, s51, 2
	s_add_u32 s6, s6, 0x100
	s_addc_u32 s7, s7, 0
	s_add_u32 s30, s30, 0x100
	s_addc_u32 s31, s31, 0
	s_add_u32 s8, s6, 0xfff80080
	s_addc_u32 s9, s7, -1
	s_cmp_eq_u32 s51, 28
	s_cselect_b32 s11, s21, s9
	s_cselect_b32 s10, s28, s8
	s_cselect_b32 s9, s19, s31
	s_cselect_b32 s8, s29, s30
	s_cmp_gt_u32 s51, 29
	s_waitcnt vmcnt(8) lgkmcnt(0)
	s_barrier
	v_mfma_f32_16x16x32_bf16 v[58:61], v[66:69], v[90:93], v[58:61]
	v_mfma_f32_16x16x32_bf16 v[46:49], v[74:77], v[90:93], v[46:49]
	v_mfma_f32_16x16x32_bf16 v[38:41], v[66:69], v[198:201], v[38:41]
	v_mfma_f32_16x16x32_bf16 v[30:33], v[74:77], v[198:201], v[30:33]
	v_mfma_f32_16x16x32_bf16 v[22:25], v[66:69], v[206:209], v[22:25]
	v_mfma_f32_16x16x32_bf16 v[18:21], v[74:77], v[206:209], v[18:21]
	v_mfma_f32_16x16x32_bf16 v[8:11], v[66:69], v[222:225], v[8:11]
	v_mfma_f32_16x16x32_bf16 v[12:15], v[74:77], v[222:225], v[12:15]
	v_mfma_f32_16x16x32_bf16 v[58:61], v[70:73], v[194:197], v[58:61]
	v_mfma_f32_16x16x32_bf16 v[46:49], v[78:81], v[194:197], v[46:49]
	v_mfma_f32_16x16x32_bf16 v[38:41], v[70:73], v[202:205], v[38:41]
	v_mfma_f32_16x16x32_bf16 v[30:33], v[78:81], v[202:205], v[30:33]
	v_mfma_f32_16x16x32_bf16 v[22:25], v[70:73], v[210:213], v[22:25]
	v_mfma_f32_16x16x32_bf16 v[18:21], v[78:81], v[210:213], v[18:21]
	v_mfma_f32_16x16x32_bf16 v[8:11], v[70:73], v[230:233], v[8:11]
	v_mfma_f32_16x16x32_bf16 v[12:15], v[78:81], v[230:233], v[12:15]
	v_mfma_f32_16x16x32_bf16 v[54:57], v[82:85], v[90:93], v[54:57]
	v_mfma_f32_16x16x32_bf16 v[94:97], v[86:89], v[194:197], v[54:57]
	v_mfma_f32_16x16x32_bf16 v[54:57], v[170:173], v[90:93], v[62:65]
	v_mfma_f32_16x16x32_bf16 v[50:53], v[82:85], v[198:201], v[50:53]
	v_mfma_f32_16x16x32_bf16 v[42:45], v[170:173], v[198:201], v[42:45]
	v_mfma_f32_16x16x32_bf16 v[34:37], v[82:85], v[206:209], v[34:37]
	v_mfma_f32_16x16x32_bf16 v[26:29], v[170:173], v[206:209], v[26:29]
	v_mfma_f32_16x16x32_bf16 v[0:3], v[82:85], v[222:225], v[0:3]
	v_mfma_f32_16x16x32_bf16 v[4:7], v[170:173], v[222:225], v[4:7]
	v_mfma_f32_16x16x32_bf16 v[90:93], v[184:187], v[194:197], v[54:57]
	v_mfma_f32_16x16x32_bf16 v[50:53], v[86:89], v[202:205], v[50:53]
	v_mfma_f32_16x16x32_bf16 v[42:45], v[184:187], v[202:205], v[42:45]
	v_mfma_f32_16x16x32_bf16 v[34:37], v[86:89], v[210:213], v[34:37]
	v_mfma_f32_16x16x32_bf16 v[26:29], v[184:187], v[210:213], v[26:29]
	v_mfma_f32_16x16x32_bf16 v[0:3], v[86:89], v[230:233], v[0:3]
	v_mfma_f32_16x16x32_bf16 v[4:7], v[184:187], v[230:233], v[4:7]
	s_barrier
	s_cbranch_scc0 .LBB0_68
	s_and_b64 vcc, exec, s[16:17]
	s_cbranch_vccz .LBB0_71
	s_barrier

.LBB0_107:
	s_ashr_i32 s9, s8, 31
	s_lshl_b64 s[10:11], s[8:9], 20
	s_add_u32 s10, s20, s10
	s_addc_u32 s11, s21, s11
	s_and_b64 s[12:13], s[4:5], exec
	s_cselect_b32 s9, s11, s15
	s_cselect_b32 s40, s10, s14
	s_ashr_i32 s7, s6, 31
	s_lshl_b64 s[12:13], s[6:7], 20
	s_add_u32 s12, s22, s12
	s_addc_u32 s13, s23, s13
	s_and_b64 s[18:19], s[4:5], exec
	s_cselect_b32 s7, s13, s17
	s_cselect_b32 s41, s12, s16
	s_add_u32 s14, s14, 0x80080
	s_addc_u32 s15, s15, 0
	s_add_u32 s42, s16, 0x100
	v_mov_b32_e32 v0, 0
	s_addc_u32 s43, s17, 0
	s_mov_b32 s44, -2
	v_mov_b32_e32 v1, v0
	v_mov_b32_e32 v2, v0
	v_mov_b32_e32 v3, v0
	v_mov_b32_e32 v26, v0
	v_mov_b32_e32 v27, v0
	v_mov_b32_e32 v28, v0
	v_mov_b32_e32 v29, v0
	v_mov_b32_e32 v4, v0
	v_mov_b32_e32 v5, v0
	v_mov_b32_e32 v6, v0
	v_mov_b32_e32 v7, v0
	v_mov_b32_e32 v34, v0
	v_mov_b32_e32 v35, v0
	v_mov_b32_e32 v36, v0
	v_mov_b32_e32 v37, v0
	v_mov_b32_e32 v8, v0
	v_mov_b32_e32 v9, v0
	v_mov_b32_e32 v10, v0
	v_mov_b32_e32 v11, v0
	v_mov_b32_e32 v38, v0
	v_mov_b32_e32 v39, v0
	v_mov_b32_e32 v40, v0
	v_mov_b32_e32 v41, v0
	v_mov_b32_e32 v12, v0
	v_mov_b32_e32 v13, v0
	v_mov_b32_e32 v14, v0
	v_mov_b32_e32 v15, v0
	v_mov_b32_e32 v46, v0
	v_mov_b32_e32 v47, v0
	v_mov_b32_e32 v48, v0
	v_mov_b32_e32 v49, v0
	v_mov_b32_e32 v62, v0
	v_mov_b32_e32 v63, v0
	v_mov_b32_e32 v64, v0
	v_mov_b32_e32 v65, v0
	v_mov_b32_e32 v98, v0
	v_mov_b32_e32 v99, v0
	v_mov_b32_e32 v100, v0
	v_mov_b32_e32 v101, v0
	s_waitcnt vmcnt(0)
	v_mov_b32_e32 v70, v0
	v_mov_b32_e32 v71, v0
	v_mov_b32_e32 v72, v0
	v_mov_b32_e32 v73, v0
	v_mov_b32_e32 v102, v0
	v_mov_b32_e32 v103, v0
	v_mov_b32_e32 v104, v0
	v_mov_b32_e32 v105, v0
	v_mov_b32_e32 v74, v0
	v_mov_b32_e32 v75, v0
	v_mov_b32_e32 v76, v0
	v_mov_b32_e32 v77, v0
	v_mov_b32_e32 v106, v0
	v_mov_b32_e32 v107, v0
	v_mov_b32_e32 v108, v0
	v_mov_b32_e32 v109, v0
	v_mov_b32_e32 v78, v0
	v_mov_b32_e32 v79, v0
	v_mov_b32_e32 v80, v0
	v_mov_b32_e32 v81, v0
	v_mov_b32_e32 v110, v0
	v_mov_b32_e32 v111, v0
	v_mov_b32_e32 v112, v0
	v_mov_b32_e32 v113, v0
	v_mov_b32_e32 v18, v0
	v_mov_b32_e32 v19, v0
	v_mov_b32_e32 v20, v0
	v_mov_b32_e32 v21, v0
	v_mov_b32_e32 v50, v0
	v_mov_b32_e32 v51, v0
	v_mov_b32_e32 v52, v0
	v_mov_b32_e32 v53, v0
	v_mov_b32_e32 v22, v0
	v_mov_b32_e32 v23, v0
	v_mov_b32_e32 v24, v0
	v_mov_b32_e32 v25, v0
	v_mov_b32_e32 v54, v0
	v_mov_b32_e32 v55, v0
	v_mov_b32_e32 v56, v0
	v_mov_b32_e32 v57, v0
	v_mov_b32_e32 v30, v0
	v_mov_b32_e32 v31, v0
	v_mov_b32_e32 v32, v0
	v_mov_b32_e32 v33, v0
	v_mov_b32_e32 v58, v0
	v_mov_b32_e32 v59, v0
	v_mov_b32_e32 v60, v0
	v_mov_b32_e32 v61, v0
	v_mov_b32_e32 v42, v0
	v_mov_b32_e32 v43, v0
	v_mov_b32_e32 v44, v0
	v_mov_b32_e32 v45, v0
	v_mov_b32_e32 v66, v0
	v_mov_b32_e32 v67, v0
	v_mov_b32_e32 v68, v0
	v_mov_b32_e32 v69, v0
	v_mov_b32_e32 v82, v0
	v_mov_b32_e32 v83, v0
	v_mov_b32_e32 v84, v0
	v_mov_b32_e32 v85, v0
	v_mov_b32_e32 v114, v0
	v_mov_b32_e32 v115, v0
	v_mov_b32_e32 v116, v0
	v_mov_b32_e32 v117, v0
	v_mov_b32_e32 v86, v0
	v_mov_b32_e32 v87, v0
	v_mov_b32_e32 v88, v0
	v_mov_b32_e32 v89, v0
	v_mov_b32_e32 v118, v0
	v_mov_b32_e32 v119, v0
	v_mov_b32_e32 v120, v0
	v_mov_b32_e32 v121, v0
	v_mov_b32_e32 v90, v0
	v_mov_b32_e32 v91, v0
	v_mov_b32_e32 v92, v0
	v_mov_b32_e32 v93, v0
	v_mov_b32_e32 v122, v0
	v_mov_b32_e32 v123, v0
	v_mov_b32_e32 v124, v0
	v_mov_b32_e32 v125, v0
	v_mov_b32_e32 v94, v0
	v_mov_b32_e32 v95, v0
	v_mov_b32_e32 v96, v0
	v_mov_b32_e32 v97, v0
	v_mov_b32_e32 v126, v0
	v_mov_b32_e32 v127, v0
	v_mov_b32_e32 v128, v0
	v_mov_b32_e32 v129, v0
	v_add_u32_e32 v170, 0x10000, v207
	v_add_u32_e32 v171, 0x14000, v207
	v_add_u32_e32 v172, 0x18000, v207
	v_add_u32_e32 v173, 0x1c000, v207
	s_add_u32 s16, s14, 0xfff80080
	s_addc_u32 s17, s15, -1
	s_cmp_eq_u32 s44, 28
	s_cselect_b32 s19, s9, s17
	s_cselect_b32 s18, s40, s16
	s_cselect_b32 s17, s7, s43
	s_cselect_b32 s16, s41, s42
.LBB0_108:
	ds_read_b128 v[130:133], v170
	ds_read_b128 v[134:137], v170 offset:1024
	ds_read_b128 v[138:141], v170 offset:2048
	ds_read_b128 v[142:145], v170 offset:3072
	ds_read_b128 v[146:149], v171
	ds_read_b128 v[150:153], v171 offset:1024
	ds_read_b128 v[154:157], v171 offset:2048
	ds_read_b128 v[158:161], v171 offset:3072
	ds_read_b128 v[162:165], v208
	ds_read_b128 v[166:169], v208 offset:1024
	ds_read_b128 v[184:187], v208 offset:2048
	ds_read_b128 v[188:191], v208 offset:3072
	ds_read_b128 v[192:195], v208 offset:4096
	s_add_i32 m0, s25, 0xc000
	ds_read_b128 v[196:199], v208 offset:5120
	global_load_lds_dwordx4 v180, s[14:15]
	s_add_i32 m0, s25, 0xe000
	ds_read_b128 v[200:203], v208 offset:6144
	global_load_lds_dwordx4 v182, s[14:15]
	ds_read_b128 v[210:213], v208 offset:7168
	s_waitcnt vmcnt(8) lgkmcnt(0)
	s_barrier
	v_mfma_f32_16x16x32_bf16 v[126:129], v[130:133], v[162:165], v[126:129]
	v_mfma_f32_16x16x32_bf16 v[94:97], v[138:141], v[162:165], v[94:97]
	v_mfma_f32_16x16x32_bf16 v[122:125], v[130:133], v[184:187], v[122:125]
	v_mfma_f32_16x16x32_bf16 v[90:93], v[138:141], v[184:187], v[90:93]
	v_mfma_f32_16x16x32_bf16 v[118:121], v[130:133], v[192:195], v[118:121]
	v_mfma_f32_16x16x32_bf16 v[86:89], v[138:141], v[192:195], v[86:89]
	v_mfma_f32_16x16x32_bf16 v[114:117], v[130:133], v[200:203], v[114:117]
	v_mfma_f32_16x16x32_bf16 v[82:85], v[138:141], v[200:203], v[82:85]
	v_mfma_f32_16x16x32_bf16 v[126:129], v[134:137], v[166:169], v[126:129]
	v_mfma_f32_16x16x32_bf16 v[94:97], v[142:145], v[166:169], v[94:97]
	v_mfma_f32_16x16x32_bf16 v[122:125], v[134:137], v[188:191], v[122:125]
	v_mfma_f32_16x16x32_bf16 v[90:93], v[142:145], v[188:191], v[90:93]
	v_mfma_f32_16x16x32_bf16 v[118:121], v[134:137], v[196:199], v[118:121]
	v_mfma_f32_16x16x32_bf16 v[86:89], v[142:145], v[196:199], v[86:89]
	v_mfma_f32_16x16x32_bf16 v[114:117], v[134:137], v[210:213], v[114:117]
	v_mfma_f32_16x16x32_bf16 v[82:85], v[142:145], v[210:213], v[82:85]
	v_mfma_f32_16x16x32_bf16 v[66:69], v[146:149], v[162:165], v[66:69]
	v_mfma_f32_16x16x32_bf16 v[42:45], v[154:157], v[162:165], v[42:45]
	v_mfma_f32_16x16x32_bf16 v[58:61], v[146:149], v[184:187], v[58:61]
	v_mfma_f32_16x16x32_bf16 v[30:33], v[154:157], v[184:187], v[30:33]
	v_mfma_f32_16x16x32_bf16 v[54:57], v[146:149], v[192:195], v[54:57]
	v_mfma_f32_16x16x32_bf16 v[22:25], v[154:157], v[192:195], v[22:25]
	v_mfma_f32_16x16x32_bf16 v[50:53], v[146:149], v[200:203], v[50:53]
	v_mfma_f32_16x16x32_bf16 v[18:21], v[154:157], v[200:203], v[18:21]
	v_mfma_f32_16x16x32_bf16 v[66:69], v[150:153], v[166:169], v[66:69]
	v_mfma_f32_16x16x32_bf16 v[42:45], v[158:161], v[166:169], v[42:45]
	v_mfma_f32_16x16x32_bf16 v[58:61], v[150:153], v[188:191], v[58:61]
	v_mfma_f32_16x16x32_bf16 v[30:33], v[158:161], v[188:191], v[30:33]
	v_mfma_f32_16x16x32_bf16 v[54:57], v[150:153], v[196:199], v[54:57]
	v_mfma_f32_16x16x32_bf16 v[22:25], v[158:161], v[196:199], v[22:25]
	v_mfma_f32_16x16x32_bf16 v[50:53], v[150:153], v[210:213], v[50:53]
	v_mfma_f32_16x16x32_bf16 v[18:21], v[158:161], v[210:213], v[18:21]
	s_barrier
	ds_read_b128 v[162:165], v208 offset:16384
	s_add_i32 m0, s24, 0x10000
	ds_read_b128 v[166:169], v208 offset:17408
	global_load_lds_dwordx4 v178, s[16:17]
	s_add_i32 m0, s24, 0x12000
	s_add_u32 s46, s16, 0x80000
	s_addc_u32 s47, s17, 0
	ds_read_b128 v[184:187], v208 offset:18432
	global_load_lds_dwordx4 v176, s[16:17]
	s_add_i32 m0, s24, 0x14000
	ds_read_b128 v[188:191], v208 offset:19456
	global_load_lds_dwordx4 v178, s[46:47]
	s_add_i32 m0, s24, 0x16000
	ds_read_b128 v[192:195], v208 offset:20480
	global_load_lds_dwordx4 v176, s[46:47]
	s_mov_b32 m0, s25
	ds_read_b128 v[196:199], v208 offset:21504
	global_load_lds_dwordx4 v178, s[18:19]
	s_mov_b32 m0, s26
	ds_read_b128 v[200:203], v208 offset:22528
	global_load_lds_dwordx4 v176, s[18:19]
	ds_read_b128 v[210:213], v208 offset:23552
	s_waitcnt vmcnt(8) lgkmcnt(0)
	s_barrier
	v_mfma_f32_16x16x32_bf16 v[110:113], v[130:133], v[162:165], v[110:113]
	v_mfma_f32_16x16x32_bf16 v[78:81], v[138:141], v[162:165], v[78:81]
	v_mfma_f32_16x16x32_bf16 v[106:109], v[130:133], v[184:187], v[106:109]
	v_mfma_f32_16x16x32_bf16 v[74:77], v[138:141], v[184:187], v[74:77]
	v_mfma_f32_16x16x32_bf16 v[102:105], v[130:133], v[192:195], v[102:105]
	v_mfma_f32_16x16x32_bf16 v[70:73], v[138:141], v[192:195], v[70:73]
	v_mfma_f32_16x16x32_bf16 v[98:101], v[130:133], v[200:203], v[98:101]
	v_mfma_f32_16x16x32_bf16 v[62:65], v[138:141], v[200:203], v[62:65]
	v_mfma_f32_16x16x32_bf16 v[110:113], v[134:137], v[166:169], v[110:113]
	v_mfma_f32_16x16x32_bf16 v[78:81], v[142:145], v[166:169], v[78:81]
	v_mfma_f32_16x16x32_bf16 v[106:109], v[134:137], v[188:191], v[106:109]
	v_mfma_f32_16x16x32_bf16 v[74:77], v[142:145], v[188:191], v[74:77]
	v_mfma_f32_16x16x32_bf16 v[102:105], v[134:137], v[196:199], v[102:105]
	v_mfma_f32_16x16x32_bf16 v[70:73], v[142:145], v[196:199], v[70:73]
	v_mfma_f32_16x16x32_bf16 v[98:101], v[134:137], v[210:213], v[98:101]
	v_mfma_f32_16x16x32_bf16 v[62:65], v[142:145], v[210:213], v[62:65]
	v_mfma_f32_16x16x32_bf16 v[46:49], v[146:149], v[162:165], v[46:49]
	v_mfma_f32_16x16x32_bf16 v[12:15], v[154:157], v[162:165], v[12:15]
	v_mfma_f32_16x16x32_bf16 v[38:41], v[146:149], v[184:187], v[38:41]
	v_mfma_f32_16x16x32_bf16 v[8:11], v[154:157], v[184:187], v[8:11]
	v_mfma_f32_16x16x32_bf16 v[34:37], v[146:149], v[192:195], v[34:37]
	v_mfma_f32_16x16x32_bf16 v[4:7], v[154:157], v[192:195], v[4:7]
	v_mfma_f32_16x16x32_bf16 v[26:29], v[146:149], v[200:203], v[26:29]
	v_mfma_f32_16x16x32_bf16 v[0:3], v[154:157], v[200:203], v[0:3]
	v_mfma_f32_16x16x32_bf16 v[46:49], v[150:153], v[166:169], v[46:49]
	v_mfma_f32_16x16x32_bf16 v[12:15], v[158:161], v[166:169], v[12:15]
	v_mfma_f32_16x16x32_bf16 v[38:41], v[150:153], v[188:191], v[38:41]
	v_mfma_f32_16x16x32_bf16 v[8:11], v[158:161], v[188:191], v[8:11]
	v_mfma_f32_16x16x32_bf16 v[34:37], v[150:153], v[196:199], v[34:37]
	v_mfma_f32_16x16x32_bf16 v[4:7], v[158:161], v[196:199], v[4:7]
	v_mfma_f32_16x16x32_bf16 v[26:29], v[150:153], v[210:213], v[26:29]
	v_mfma_f32_16x16x32_bf16 v[0:3], v[158:161], v[210:213], v[0:3]
	s_barrier
	s_add_u32 s100, s18, 0x80000
	s_addc_u32 s101, s19, 0
	ds_read_b128 v[130:133], v172
	ds_read_b128 v[134:137], v172 offset:1024
	ds_read_b128 v[138:141], v172 offset:2048
	ds_read_b128 v[142:145], v172 offset:3072
	ds_read_b128 v[146:149], v173
	ds_read_b128 v[150:153], v173 offset:1024
	ds_read_b128 v[154:157], v173 offset:2048
	ds_read_b128 v[158:161], v173 offset:3072
	ds_read_b128 v[162:165], v208 offset:32768
	ds_read_b128 v[166:169], v208 offset:33792
	ds_read_b128 v[184:187], v208 offset:34816
	ds_read_b128 v[188:191], v208 offset:35840
	ds_read_b128 v[192:195], v208 offset:36864
	s_mov_b32 m0, s27
	ds_read_b128 v[196:199], v208 offset:37888
	global_load_lds_dwordx4 v178, s[100:101]
	s_mov_b32 m0, s28
	ds_read_b128 v[200:203], v208 offset:38912
	global_load_lds_dwordx4 v176, s[100:101]
	ds_read_b128 v[210:213], v208 offset:39936
	s_waitcnt vmcnt(8) lgkmcnt(0)
	s_barrier
	v_mfma_f32_16x16x32_bf16 v[126:129], v[130:133], v[162:165], v[126:129]
	v_mfma_f32_16x16x32_bf16 v[94:97], v[138:141], v[162:165], v[94:97]
	v_mfma_f32_16x16x32_bf16 v[122:125], v[130:133], v[184:187], v[122:125]
	v_mfma_f32_16x16x32_bf16 v[90:93], v[138:141], v[184:187], v[90:93]
	v_mfma_f32_16x16x32_bf16 v[118:121], v[130:133], v[192:195], v[118:121]
	v_mfma_f32_16x16x32_bf16 v[86:89], v[138:141], v[192:195], v[86:89]
	v_mfma_f32_16x16x32_bf16 v[114:117], v[130:133], v[200:203], v[114:117]
	v_mfma_f32_16x16x32_bf16 v[82:85], v[138:141], v[200:203], v[82:85]
	v_mfma_f32_16x16x32_bf16 v[126:129], v[134:137], v[166:169], v[126:129]
	v_mfma_f32_16x16x32_bf16 v[94:97], v[142:145], v[166:169], v[94:97]
	v_mfma_f32_16x16x32_bf16 v[122:125], v[134:137], v[188:191], v[122:125]
	v_mfma_f32_16x16x32_bf16 v[90:93], v[142:145], v[188:191], v[90:93]
	v_mfma_f32_16x16x32_bf16 v[118:121], v[134:137], v[196:199], v[118:121]
	v_mfma_f32_16x16x32_bf16 v[86:89], v[142:145], v[196:199], v[86:89]
	v_mfma_f32_16x16x32_bf16 v[114:117], v[134:137], v[210:213], v[114:117]
	v_mfma_f32_16x16x32_bf16 v[82:85], v[142:145], v[210:213], v[82:85]
	v_mfma_f32_16x16x32_bf16 v[66:69], v[146:149], v[162:165], v[66:69]
	v_mfma_f32_16x16x32_bf16 v[42:45], v[154:157], v[162:165], v[42:45]
	v_mfma_f32_16x16x32_bf16 v[58:61], v[146:149], v[184:187], v[58:61]
	v_mfma_f32_16x16x32_bf16 v[30:33], v[154:157], v[184:187], v[30:33]
	v_mfma_f32_16x16x32_bf16 v[54:57], v[146:149], v[192:195], v[54:57]
	v_mfma_f32_16x16x32_bf16 v[22:25], v[154:157], v[192:195], v[22:25]
	v_mfma_f32_16x16x32_bf16 v[50:53], v[146:149], v[200:203], v[50:53]
	v_mfma_f32_16x16x32_bf16 v[18:21], v[154:157], v[200:203], v[18:21]
	v_mfma_f32_16x16x32_bf16 v[66:69], v[150:153], v[166:169], v[66:69]
	v_mfma_f32_16x16x32_bf16 v[42:45], v[158:161], v[166:169], v[42:45]
	v_mfma_f32_16x16x32_bf16 v[58:61], v[150:153], v[188:191], v[58:61]
	v_mfma_f32_16x16x32_bf16 v[30:33], v[158:161], v[188:191], v[30:33]
	v_mfma_f32_16x16x32_bf16 v[54:57], v[150:153], v[196:199], v[54:57]
	v_mfma_f32_16x16x32_bf16 v[22:25], v[158:161], v[196:199], v[22:25]
	v_mfma_f32_16x16x32_bf16 v[50:53], v[150:153], v[210:213], v[50:53]
	v_mfma_f32_16x16x32_bf16 v[18:21], v[158:161], v[210:213], v[18:21]
	s_barrier
	ds_read_b128 v[162:165], v208 offset:49152
	s_add_i32 m0, s24, 0x17f80
	ds_read_b128 v[166:169], v208 offset:50176
	global_load_lds_dwordx4 v178, s[16:17] offset:128
	s_add_i32 m0, s24, 0x19f80
	ds_read_b128 v[184:187], v208 offset:51200
	global_load_lds_dwordx4 v176, s[16:17] offset:128
	s_add_i32 m0, s24, 0x1bf80
	ds_read_b128 v[188:191], v208 offset:52224
	global_load_lds_dwordx4 v178, s[46:47] offset:128
	s_add_i32 m0, s24, 0x1df80
	ds_read_b128 v[192:195], v208 offset:53248
	global_load_lds_dwordx4 v176, s[46:47] offset:128
	s_add_i32 m0, s35, 0xffffff80
	ds_read_b128 v[196:199], v208 offset:54272
	global_load_lds_dwordx4 v178, s[18:19] offset:128
	s_add_i32 m0, s36, 0xffffff80
	ds_read_b128 v[200:203], v208 offset:55296
	global_load_lds_dwordx4 v176, s[18:19] offset:128
	ds_read_b128 v[210:213], v208 offset:56320
	s_add_i32 s44, s44, 2
	s_add_u32 s14, s14, 0x100
	s_addc_u32 s15, s15, 0
	s_add_u32 s42, s42, 0x100
	s_addc_u32 s43, s43, 0
	s_add_u32 s16, s14, 0xfff80080
	s_addc_u32 s17, s15, -1
	s_cmp_eq_u32 s44, 28
	s_cselect_b32 s19, s9, s17
	s_cselect_b32 s18, s40, s16
	s_cselect_b32 s17, s7, s43
	s_cselect_b32 s16, s41, s42
	s_cmp_gt_u32 s44, 29
	s_waitcnt vmcnt(8) lgkmcnt(0)
	s_barrier
	v_mfma_f32_16x16x32_bf16 v[110:113], v[130:133], v[162:165], v[110:113]
	v_mfma_f32_16x16x32_bf16 v[78:81], v[138:141], v[162:165], v[78:81]
	v_mfma_f32_16x16x32_bf16 v[106:109], v[130:133], v[184:187], v[106:109]
	v_mfma_f32_16x16x32_bf16 v[74:77], v[138:141], v[184:187], v[74:77]
	v_mfma_f32_16x16x32_bf16 v[102:105], v[130:133], v[192:195], v[102:105]
	v_mfma_f32_16x16x32_bf16 v[70:73], v[138:141], v[192:195], v[70:73]
	v_mfma_f32_16x16x32_bf16 v[98:101], v[130:133], v[200:203], v[98:101]
	v_mfma_f32_16x16x32_bf16 v[62:65], v[138:141], v[200:203], v[62:65]
	v_mfma_f32_16x16x32_bf16 v[110:113], v[134:137], v[166:169], v[110:113]
	v_mfma_f32_16x16x32_bf16 v[78:81], v[142:145], v[166:169], v[78:81]
	v_mfma_f32_16x16x32_bf16 v[106:109], v[134:137], v[188:191], v[106:109]
	v_mfma_f32_16x16x32_bf16 v[74:77], v[142:145], v[188:191], v[74:77]
	v_mfma_f32_16x16x32_bf16 v[102:105], v[134:137], v[196:199], v[102:105]
	v_mfma_f32_16x16x32_bf16 v[70:73], v[142:145], v[196:199], v[70:73]
	v_mfma_f32_16x16x32_bf16 v[98:101], v[134:137], v[210:213], v[98:101]
	v_mfma_f32_16x16x32_bf16 v[62:65], v[142:145], v[210:213], v[62:65]
	v_mfma_f32_16x16x32_bf16 v[46:49], v[146:149], v[162:165], v[46:49]
	v_mfma_f32_16x16x32_bf16 v[12:15], v[154:157], v[162:165], v[12:15]
	v_mfma_f32_16x16x32_bf16 v[38:41], v[146:149], v[184:187], v[38:41]
	v_mfma_f32_16x16x32_bf16 v[8:11], v[154:157], v[184:187], v[8:11]
	v_mfma_f32_16x16x32_bf16 v[34:37], v[146:149], v[192:195], v[34:37]
	v_mfma_f32_16x16x32_bf16 v[4:7], v[154:157], v[192:195], v[4:7]
	v_mfma_f32_16x16x32_bf16 v[26:29], v[146:149], v[200:203], v[26:29]
	v_mfma_f32_16x16x32_bf16 v[0:3], v[154:157], v[200:203], v[0:3]
	v_mfma_f32_16x16x32_bf16 v[46:49], v[150:153], v[166:169], v[46:49]
	v_mfma_f32_16x16x32_bf16 v[12:15], v[158:161], v[166:169], v[12:15]
	v_mfma_f32_16x16x32_bf16 v[38:41], v[150:153], v[188:191], v[38:41]
	v_mfma_f32_16x16x32_bf16 v[8:11], v[158:161], v[188:191], v[8:11]
	v_mfma_f32_16x16x32_bf16 v[34:37], v[150:153], v[196:199], v[34:37]
	v_mfma_f32_16x16x32_bf16 v[4:7], v[158:161], v[196:199], v[4:7]
	v_mfma_f32_16x16x32_bf16 v[26:29], v[150:153], v[210:213], v[26:29]
	v_mfma_f32_16x16x32_bf16 v[0:3], v[158:161], v[210:213], v[0:3]
	s_barrier
	s_cbranch_scc0 .LBB0_108
	s_and_b64 vcc, exec, s[2:3]
	s_movk_i32 s44, 0x1000
	s_cbranch_vccz .LBB0_111
	s_barrier

.LBB0_551:
	s_ashr_i32 s19, s18, 31
	s_lshl_b64 s[20:21], s[18:19], 18
	s_add_u32 s17, s0, s20
	s_addc_u32 s19, s1, s21
	s_cmp_gt_i32 s16, 1
	s_cselect_b32 s20, 0x2000000, 0
	s_add_u32 s20, s17, s20
	s_addc_u32 s21, s19, 0
	s_and_b64 s[22:23], s[4:5], exec
	s_cselect_b32 s19, s21, s7
	s_cselect_b32 s42, s20, s6
	s_ashr_i32 s17, s16, 31
	s_lshl_b64 s[22:23], s[16:17], 18
	s_add_u32 s22, s28, s22
	s_addc_u32 s23, s29, s23
	s_and_b64 s[24:25], s[4:5], exec
	s_cselect_b32 s17, s23, s9
	s_cselect_b32 s43, s22, s8
	s_add_u32 s6, s6, 0x20080
	s_addc_u32 s7, s7, 0
	s_add_u32 s44, s8, 0x100
	v_mov_b32_e32 v0, 0
	s_addc_u32 s45, s9, 0
	s_mov_b32 s46, -2
	v_mov_b32_e32 v1, v0
	v_mov_b32_e32 v2, v0
	v_mov_b32_e32 v3, v0
	v_mov_b32_e32 v4, v0
	v_mov_b32_e32 v5, v0
	v_mov_b32_e32 v6, v0
	v_mov_b32_e32 v7, v0
	v_mov_b32_e32 v8, v0
	v_mov_b32_e32 v9, v0
	v_mov_b32_e32 v10, v0
	v_mov_b32_e32 v11, v0
	v_mov_b32_e32 v12, v0
	v_mov_b32_e32 v13, v0
	v_mov_b32_e32 v14, v0
	v_mov_b32_e32 v15, v0
	v_mov_b32_e32 v18, v0
	v_mov_b32_e32 v19, v0
	v_mov_b32_e32 v20, v0
	v_mov_b32_e32 v21, v0
	v_mov_b32_e32 v22, v0
	v_mov_b32_e32 v23, v0
	v_mov_b32_e32 v24, v0
	v_mov_b32_e32 v25, v0
	v_mov_b32_e32 v26, v0
	v_mov_b32_e32 v27, v0
	v_mov_b32_e32 v28, v0
	v_mov_b32_e32 v29, v0
	v_mov_b32_e32 v30, v0
	v_mov_b32_e32 v31, v0
	v_mov_b32_e32 v32, v0
	v_mov_b32_e32 v33, v0
	s_waitcnt vmcnt(0)
	v_mov_b32_e32 v78, v0
	v_mov_b32_e32 v79, v0
	v_mov_b32_e32 v80, v0
	v_mov_b32_e32 v81, v0
	v_mov_b32_e32 v82, v0
	v_mov_b32_e32 v83, v0
	v_mov_b32_e32 v84, v0
	v_mov_b32_e32 v85, v0
	v_mov_b32_e32 v90, v0
	v_mov_b32_e32 v91, v0
	v_mov_b32_e32 v92, v0
	v_mov_b32_e32 v93, v0
	v_mov_b32_e32 v94, v0
	v_mov_b32_e32 v95, v0
	v_mov_b32_e32 v96, v0
	v_mov_b32_e32 v97, v0
	v_mov_b32_e32 v98, v0
	v_mov_b32_e32 v99, v0
	v_mov_b32_e32 v100, v0
	v_mov_b32_e32 v101, v0
	v_mov_b32_e32 v102, v0
	v_mov_b32_e32 v103, v0
	v_mov_b32_e32 v104, v0
	v_mov_b32_e32 v105, v0
	v_mov_b32_e32 v106, v0
	v_mov_b32_e32 v107, v0
	v_mov_b32_e32 v108, v0
	v_mov_b32_e32 v109, v0
	v_mov_b32_e32 v110, v0
	v_mov_b32_e32 v111, v0
	v_mov_b32_e32 v112, v0
	v_mov_b32_e32 v113, v0
	v_mov_b32_e32 v34, v0
	v_mov_b32_e32 v35, v0
	v_mov_b32_e32 v36, v0
	v_mov_b32_e32 v37, v0
	v_mov_b32_e32 v38, v0
	v_mov_b32_e32 v39, v0
	v_mov_b32_e32 v40, v0
	v_mov_b32_e32 v41, v0
	v_mov_b32_e32 v42, v0
	v_mov_b32_e32 v43, v0
	v_mov_b32_e32 v44, v0
	v_mov_b32_e32 v45, v0
	v_mov_b32_e32 v46, v0
	v_mov_b32_e32 v47, v0
	v_mov_b32_e32 v48, v0
	v_mov_b32_e32 v49, v0
	v_mov_b32_e32 v50, v0
	v_mov_b32_e32 v51, v0
	v_mov_b32_e32 v52, v0
	v_mov_b32_e32 v53, v0
	v_mov_b32_e32 v54, v0
	v_mov_b32_e32 v55, v0
	v_mov_b32_e32 v56, v0
	v_mov_b32_e32 v57, v0
	v_mov_b32_e32 v62, v0
	v_mov_b32_e32 v63, v0
	v_mov_b32_e32 v64, v0
	v_mov_b32_e32 v65, v0
	v_mov_b32_e32 v66, v0
	v_mov_b32_e32 v67, v0
	v_mov_b32_e32 v68, v0
	v_mov_b32_e32 v69, v0
	v_mov_b32_e32 v114, v0
	v_mov_b32_e32 v115, v0
	v_mov_b32_e32 v116, v0
	v_mov_b32_e32 v117, v0
	v_mov_b32_e32 v118, v0
	v_mov_b32_e32 v119, v0
	v_mov_b32_e32 v120, v0
	v_mov_b32_e32 v121, v0
	v_mov_b32_e32 v130, v0
	v_mov_b32_e32 v131, v0
	v_mov_b32_e32 v132, v0
	v_mov_b32_e32 v133, v0
	v_mov_b32_e32 v134, v0
	v_mov_b32_e32 v135, v0
	v_mov_b32_e32 v136, v0
	v_mov_b32_e32 v137, v0
	v_mov_b32_e32 v138, v0
	v_mov_b32_e32 v139, v0
	v_mov_b32_e32 v140, v0
	v_mov_b32_e32 v141, v0
	v_mov_b32_e32 v142, v0
	v_mov_b32_e32 v143, v0
	v_mov_b32_e32 v144, v0
	v_mov_b32_e32 v145, v0
	v_mov_b32_e32 v146, v0
	v_mov_b32_e32 v147, v0
	v_mov_b32_e32 v148, v0
	v_mov_b32_e32 v149, v0
	v_mov_b32_e32 v150, v0
	v_mov_b32_e32 v151, v0
	v_mov_b32_e32 v152, v0
	v_mov_b32_e32 v153, v0
	v_add_u32_e32 v168, 0x10000, v184
	v_add_u32_e32 v169, 0x14000, v184
	v_add_u32_e32 v170, 0x18000, v184
	v_add_u32_e32 v171, 0x1c000, v184
	s_add_u32 s8, s6, 0xfffe0080
	s_addc_u32 s9, s7, -1
	s_cmp_eq_u32 s46, 4
	s_cselect_b32 s25, s19, s9
	s_cselect_b32 s24, s42, s8
	s_cselect_b32 s9, s17, s45
	s_cselect_b32 s8, s43, s44
.LBB0_552:
	ds_read_b128 v[58:61], v168
	ds_read_b128 v[70:73], v168 offset:1024
	ds_read_b128 v[74:77], v168 offset:2048
	ds_read_b128 v[86:89], v168 offset:3072
	ds_read_b128 v[122:125], v169
	ds_read_b128 v[126:129], v169 offset:1024
	ds_read_b128 v[154:157], v169 offset:2048
	ds_read_b128 v[176:179], v169 offset:3072
	ds_read_b128 v[186:189], v185
	ds_read_b128 v[190:193], v185 offset:1024
	ds_read_b128 v[194:197], v185 offset:2048
	ds_read_b128 v[198:201], v185 offset:3072
	ds_read_b128 v[202:205], v185 offset:4096
	s_add_i32 m0, s31, 0xc000
	ds_read_b128 v[206:209], v185 offset:5120
	global_load_lds_dwordx4 v164, s[6:7]
	s_add_i32 m0, s31, 0xe000
	ds_read_b128 v[210:213], v185 offset:6144
	global_load_lds_dwordx4 v166, s[6:7]
	ds_read_b128 v[230:233], v185 offset:7168
	s_waitcnt vmcnt(8) lgkmcnt(0)
	s_barrier
	v_mfma_f32_16x16x32_bf16 v[150:153], v[58:61], v[186:189], v[150:153]
	v_mfma_f32_16x16x32_bf16 v[146:149], v[74:77], v[186:189], v[146:149]
	v_mfma_f32_16x16x32_bf16 v[142:145], v[58:61], v[194:197], v[142:145]
	v_mfma_f32_16x16x32_bf16 v[138:141], v[74:77], v[194:197], v[138:141]
	v_mfma_f32_16x16x32_bf16 v[134:137], v[58:61], v[202:205], v[134:137]
	v_mfma_f32_16x16x32_bf16 v[130:133], v[74:77], v[202:205], v[130:133]
	v_mfma_f32_16x16x32_bf16 v[118:121], v[58:61], v[210:213], v[118:121]
	v_mfma_f32_16x16x32_bf16 v[114:117], v[74:77], v[210:213], v[114:117]
	v_mfma_f32_16x16x32_bf16 v[150:153], v[70:73], v[190:193], v[150:153]
	v_mfma_f32_16x16x32_bf16 v[146:149], v[86:89], v[190:193], v[146:149]
	v_mfma_f32_16x16x32_bf16 v[142:145], v[70:73], v[198:201], v[142:145]
	v_mfma_f32_16x16x32_bf16 v[138:141], v[86:89], v[198:201], v[138:141]
	v_mfma_f32_16x16x32_bf16 v[134:137], v[70:73], v[206:209], v[134:137]
	v_mfma_f32_16x16x32_bf16 v[130:133], v[86:89], v[206:209], v[130:133]
	v_mfma_f32_16x16x32_bf16 v[118:121], v[70:73], v[230:233], v[118:121]
	v_mfma_f32_16x16x32_bf16 v[114:117], v[86:89], v[230:233], v[114:117]
	v_mfma_f32_16x16x32_bf16 v[66:69], v[122:125], v[186:189], v[66:69]
	v_mfma_f32_16x16x32_bf16 v[62:65], v[154:157], v[186:189], v[62:65]
	v_mfma_f32_16x16x32_bf16 v[54:57], v[122:125], v[194:197], v[54:57]
	v_mfma_f32_16x16x32_bf16 v[50:53], v[154:157], v[194:197], v[50:53]
	v_mfma_f32_16x16x32_bf16 v[46:49], v[122:125], v[202:205], v[46:49]
	v_mfma_f32_16x16x32_bf16 v[42:45], v[154:157], v[202:205], v[42:45]
	v_mfma_f32_16x16x32_bf16 v[38:41], v[122:125], v[210:213], v[38:41]
	v_mfma_f32_16x16x32_bf16 v[34:37], v[154:157], v[210:213], v[34:37]
	v_mfma_f32_16x16x32_bf16 v[66:69], v[126:129], v[190:193], v[66:69]
	v_mfma_f32_16x16x32_bf16 v[62:65], v[176:179], v[190:193], v[62:65]
	v_mfma_f32_16x16x32_bf16 v[54:57], v[126:129], v[198:201], v[54:57]
	v_mfma_f32_16x16x32_bf16 v[50:53], v[176:179], v[198:201], v[50:53]
	v_mfma_f32_16x16x32_bf16 v[46:49], v[126:129], v[206:209], v[46:49]
	v_mfma_f32_16x16x32_bf16 v[42:45], v[176:179], v[206:209], v[42:45]
	v_mfma_f32_16x16x32_bf16 v[38:41], v[126:129], v[230:233], v[38:41]
	v_mfma_f32_16x16x32_bf16 v[34:37], v[176:179], v[230:233], v[34:37]
	s_barrier
	ds_read_b128 v[186:189], v185 offset:16384
	s_add_i32 m0, s30, 0x10000
	ds_read_b128 v[190:193], v185 offset:17408
	global_load_lds_dwordx4 v16, s[8:9]
	s_add_i32 m0, s30, 0x12000
	s_add_u32 s48, s8, 0x20000
	s_addc_u32 s49, s9, 0
	ds_read_b128 v[194:197], v185 offset:18432
	global_load_lds_dwordx4 v158, s[8:9]
	s_add_i32 m0, s30, 0x14000
	ds_read_b128 v[198:201], v185 offset:19456
	global_load_lds_dwordx4 v16, s[48:49]
	s_add_i32 m0, s30, 0x16000
	ds_read_b128 v[202:205], v185 offset:20480
	global_load_lds_dwordx4 v158, s[48:49]
	s_mov_b32 m0, s31
	ds_read_b128 v[206:209], v185 offset:21504
	global_load_lds_dwordx4 v162, s[24:25]
	s_mov_b32 m0, s34
	ds_read_b128 v[210:213], v185 offset:22528
	global_load_lds_dwordx4 v160, s[24:25]
	ds_read_b128 v[230:233], v185 offset:23552
	s_waitcnt vmcnt(8) lgkmcnt(0)
	s_barrier
	v_mfma_f32_16x16x32_bf16 v[110:113], v[58:61], v[186:189], v[110:113]
	v_mfma_f32_16x16x32_bf16 v[106:109], v[74:77], v[186:189], v[106:109]
	v_mfma_f32_16x16x32_bf16 v[102:105], v[58:61], v[194:197], v[102:105]
	v_mfma_f32_16x16x32_bf16 v[98:101], v[74:77], v[194:197], v[98:101]
	v_mfma_f32_16x16x32_bf16 v[94:97], v[58:61], v[202:205], v[94:97]
	v_mfma_f32_16x16x32_bf16 v[90:93], v[74:77], v[202:205], v[90:93]
	v_mfma_f32_16x16x32_bf16 v[58:61], v[58:61], v[210:213], v[82:85]
	v_mfma_f32_16x16x32_bf16 v[110:113], v[70:73], v[190:193], v[110:113]
	v_mfma_f32_16x16x32_bf16 v[106:109], v[86:89], v[190:193], v[106:109]
	v_mfma_f32_16x16x32_bf16 v[102:105], v[70:73], v[198:201], v[102:105]
	v_mfma_f32_16x16x32_bf16 v[98:101], v[86:89], v[198:201], v[98:101]
	v_mfma_f32_16x16x32_bf16 v[94:97], v[70:73], v[206:209], v[94:97]
	v_mfma_f32_16x16x32_bf16 v[90:93], v[86:89], v[206:209], v[90:93]
	v_mfma_f32_16x16x32_bf16 v[58:61], v[70:73], v[230:233], v[58:61]
	v_mfma_f32_16x16x32_bf16 v[70:73], v[74:77], v[210:213], v[78:81]
	v_mfma_f32_16x16x32_bf16 v[70:73], v[86:89], v[230:233], v[70:73]
	v_mfma_f32_16x16x32_bf16 v[30:33], v[122:125], v[186:189], v[30:33]
	v_mfma_f32_16x16x32_bf16 v[26:29], v[154:157], v[186:189], v[26:29]
	v_mfma_f32_16x16x32_bf16 v[22:25], v[122:125], v[194:197], v[22:25]
	v_mfma_f32_16x16x32_bf16 v[18:21], v[154:157], v[194:197], v[18:21]
	v_mfma_f32_16x16x32_bf16 v[12:15], v[122:125], v[202:205], v[12:15]
	v_mfma_f32_16x16x32_bf16 v[8:11], v[154:157], v[202:205], v[8:11]
	v_mfma_f32_16x16x32_bf16 v[4:7], v[122:125], v[210:213], v[4:7]
	v_mfma_f32_16x16x32_bf16 v[0:3], v[154:157], v[210:213], v[0:3]
	v_mfma_f32_16x16x32_bf16 v[30:33], v[126:129], v[190:193], v[30:33]
	v_mfma_f32_16x16x32_bf16 v[26:29], v[176:179], v[190:193], v[26:29]
	v_mfma_f32_16x16x32_bf16 v[22:25], v[126:129], v[198:201], v[22:25]
	v_mfma_f32_16x16x32_bf16 v[18:21], v[176:179], v[198:201], v[18:21]
	v_mfma_f32_16x16x32_bf16 v[12:15], v[126:129], v[206:209], v[12:15]
	v_mfma_f32_16x16x32_bf16 v[8:11], v[176:179], v[206:209], v[8:11]
	v_mfma_f32_16x16x32_bf16 v[4:7], v[126:129], v[230:233], v[4:7]
	v_mfma_f32_16x16x32_bf16 v[0:3], v[176:179], v[230:233], v[0:3]
	s_barrier
	s_add_u32 s100, s24, 0x20000
	s_addc_u32 s101, s25, 0
	ds_read_b128 v[74:77], v170
	ds_read_b128 v[78:81], v170 offset:1024
	ds_read_b128 v[86:89], v170 offset:2048
	ds_read_b128 v[122:125], v170 offset:3072
	ds_read_b128 v[126:129], v171
	ds_read_b128 v[154:157], v171 offset:1024
	ds_read_b128 v[176:179], v171 offset:2048
	ds_read_b128 v[186:189], v171 offset:3072
	ds_read_b128 v[82:85], v185 offset:32768
	ds_read_b128 v[190:193], v185 offset:33792
	ds_read_b128 v[194:197], v185 offset:34816
	ds_read_b128 v[198:201], v185 offset:35840
	ds_read_b128 v[202:205], v185 offset:36864
	s_mov_b32 m0, s35
	ds_read_b128 v[206:209], v185 offset:37888
	global_load_lds_dwordx4 v162, s[100:101]
	s_mov_b32 m0, s36
	ds_read_b128 v[210:213], v185 offset:38912
	global_load_lds_dwordx4 v160, s[100:101]
	ds_read_b128 v[230:233], v185 offset:39936
	s_waitcnt vmcnt(8) lgkmcnt(0)
	s_barrier
	v_mfma_f32_16x16x32_bf16 v[150:153], v[74:77], v[82:85], v[150:153]
	v_mfma_f32_16x16x32_bf16 v[146:149], v[86:89], v[82:85], v[146:149]
	v_mfma_f32_16x16x32_bf16 v[142:145], v[74:77], v[194:197], v[142:145]
	v_mfma_f32_16x16x32_bf16 v[138:141], v[86:89], v[194:197], v[138:141]
	v_mfma_f32_16x16x32_bf16 v[134:137], v[74:77], v[202:205], v[134:137]
	v_mfma_f32_16x16x32_bf16 v[130:133], v[86:89], v[202:205], v[130:133]
	v_mfma_f32_16x16x32_bf16 v[118:121], v[74:77], v[210:213], v[118:121]
	v_mfma_f32_16x16x32_bf16 v[114:117], v[86:89], v[210:213], v[114:117]
	v_mfma_f32_16x16x32_bf16 v[150:153], v[78:81], v[190:193], v[150:153]
	v_mfma_f32_16x16x32_bf16 v[146:149], v[122:125], v[190:193], v[146:149]
	v_mfma_f32_16x16x32_bf16 v[142:145], v[78:81], v[198:201], v[142:145]
	v_mfma_f32_16x16x32_bf16 v[138:141], v[122:125], v[198:201], v[138:141]
	v_mfma_f32_16x16x32_bf16 v[134:137], v[78:81], v[206:209], v[134:137]
	v_mfma_f32_16x16x32_bf16 v[130:133], v[122:125], v[206:209], v[130:133]
	v_mfma_f32_16x16x32_bf16 v[118:121], v[78:81], v[230:233], v[118:121]
	v_mfma_f32_16x16x32_bf16 v[114:117], v[122:125], v[230:233], v[114:117]
	v_mfma_f32_16x16x32_bf16 v[66:69], v[126:129], v[82:85], v[66:69]
	v_mfma_f32_16x16x32_bf16 v[62:65], v[176:179], v[82:85], v[62:65]
	v_mfma_f32_16x16x32_bf16 v[54:57], v[126:129], v[194:197], v[54:57]
	v_mfma_f32_16x16x32_bf16 v[50:53], v[176:179], v[194:197], v[50:53]
	v_mfma_f32_16x16x32_bf16 v[46:49], v[126:129], v[202:205], v[46:49]
	v_mfma_f32_16x16x32_bf16 v[42:45], v[176:179], v[202:205], v[42:45]
	v_mfma_f32_16x16x32_bf16 v[38:41], v[126:129], v[210:213], v[38:41]
	v_mfma_f32_16x16x32_bf16 v[34:37], v[176:179], v[210:213], v[34:37]
	v_mfma_f32_16x16x32_bf16 v[66:69], v[154:157], v[190:193], v[66:69]
	v_mfma_f32_16x16x32_bf16 v[62:65], v[186:189], v[190:193], v[62:65]
	v_mfma_f32_16x16x32_bf16 v[54:57], v[154:157], v[198:201], v[54:57]
	v_mfma_f32_16x16x32_bf16 v[50:53], v[186:189], v[198:201], v[50:53]
	v_mfma_f32_16x16x32_bf16 v[46:49], v[154:157], v[206:209], v[46:49]
	v_mfma_f32_16x16x32_bf16 v[42:45], v[186:189], v[206:209], v[42:45]
	v_mfma_f32_16x16x32_bf16 v[38:41], v[154:157], v[230:233], v[38:41]
	v_mfma_f32_16x16x32_bf16 v[34:37], v[186:189], v[230:233], v[34:37]
	s_barrier
	ds_read_b128 v[190:193], v185 offset:49152
	s_add_i32 m0, s30, 0x17f80
	ds_read_b128 v[194:197], v185 offset:50176
	global_load_lds_dwordx4 v16, s[8:9] offset:128
	s_add_i32 m0, s30, 0x19f80
	ds_read_b128 v[198:201], v185 offset:51200
	global_load_lds_dwordx4 v158, s[8:9] offset:128
	s_add_i32 m0, s30, 0x1bf80
	ds_read_b128 v[202:205], v185 offset:52224
	global_load_lds_dwordx4 v16, s[48:49] offset:128
	s_add_i32 m0, s30, 0x1df80
	ds_read_b128 v[206:209], v185 offset:53248
	global_load_lds_dwordx4 v158, s[48:49] offset:128
	s_add_i32 m0, s38, 0xffffff80
	ds_read_b128 v[210:213], v185 offset:54272
	global_load_lds_dwordx4 v162, s[24:25] offset:128
	s_add_i32 m0, s39, 0xffffff80
	ds_read_b128 v[230:233], v185 offset:55296
	global_load_lds_dwordx4 v160, s[24:25] offset:128
	ds_read_b128 v[234:237], v185 offset:56320
	s_add_i32 s46, s46, 2
	s_add_u32 s6, s6, 0x100
	s_addc_u32 s7, s7, 0
	s_add_u32 s44, s44, 0x100
	s_addc_u32 s45, s45, 0
	s_add_u32 s8, s6, 0xfffe0080
	s_addc_u32 s9, s7, -1
	s_cmp_eq_u32 s46, 4
	s_cselect_b32 s25, s19, s9
	s_cselect_b32 s24, s42, s8
	s_cselect_b32 s9, s17, s45
	s_cselect_b32 s8, s43, s44
	s_cmp_gt_u32 s46, 5
	s_waitcnt vmcnt(8) lgkmcnt(0)
	s_barrier
	v_mfma_f32_16x16x32_bf16 v[82:85], v[74:77], v[190:193], v[110:113]
	v_mfma_f32_16x16x32_bf16 v[110:113], v[78:81], v[194:197], v[82:85]
	v_mfma_f32_16x16x32_bf16 v[82:85], v[86:89], v[190:193], v[106:109]
	v_mfma_f32_16x16x32_bf16 v[106:109], v[122:125], v[194:197], v[82:85]
	v_mfma_f32_16x16x32_bf16 v[82:85], v[74:77], v[198:201], v[102:105]
	v_mfma_f32_16x16x32_bf16 v[102:105], v[78:81], v[202:205], v[82:85]
	v_mfma_f32_16x16x32_bf16 v[82:85], v[86:89], v[198:201], v[98:101]
	v_mfma_f32_16x16x32_bf16 v[98:101], v[122:125], v[202:205], v[82:85]
	v_mfma_f32_16x16x32_bf16 v[82:85], v[74:77], v[206:209], v[94:97]
	v_mfma_f32_16x16x32_bf16 v[94:97], v[78:81], v[210:213], v[82:85]
	v_mfma_f32_16x16x32_bf16 v[82:85], v[86:89], v[206:209], v[90:93]
	v_mfma_f32_16x16x32_bf16 v[58:61], v[74:77], v[230:233], v[58:61]
	v_mfma_f32_16x16x32_bf16 v[90:93], v[122:125], v[210:213], v[82:85]
	v_mfma_f32_16x16x32_bf16 v[82:85], v[78:81], v[234:237], v[58:61]
	v_mfma_f32_16x16x32_bf16 v[58:61], v[86:89], v[230:233], v[70:73]
	v_mfma_f32_16x16x32_bf16 v[78:81], v[122:125], v[234:237], v[58:61]
	v_mfma_f32_16x16x32_bf16 v[30:33], v[126:129], v[190:193], v[30:33]
	v_mfma_f32_16x16x32_bf16 v[26:29], v[176:179], v[190:193], v[26:29]
	v_mfma_f32_16x16x32_bf16 v[22:25], v[126:129], v[198:201], v[22:25]
	v_mfma_f32_16x16x32_bf16 v[18:21], v[176:179], v[198:201], v[18:21]
	v_mfma_f32_16x16x32_bf16 v[12:15], v[126:129], v[206:209], v[12:15]
	v_mfma_f32_16x16x32_bf16 v[8:11], v[176:179], v[206:209], v[8:11]
	v_mfma_f32_16x16x32_bf16 v[4:7], v[126:129], v[230:233], v[4:7]
	v_mfma_f32_16x16x32_bf16 v[0:3], v[176:179], v[230:233], v[0:3]
	v_mfma_f32_16x16x32_bf16 v[30:33], v[154:157], v[194:197], v[30:33]
	v_mfma_f32_16x16x32_bf16 v[26:29], v[186:189], v[194:197], v[26:29]
	v_mfma_f32_16x16x32_bf16 v[22:25], v[154:157], v[202:205], v[22:25]
	v_mfma_f32_16x16x32_bf16 v[18:21], v[186:189], v[202:205], v[18:21]
	v_mfma_f32_16x16x32_bf16 v[12:15], v[154:157], v[210:213], v[12:15]
	v_mfma_f32_16x16x32_bf16 v[8:11], v[186:189], v[210:213], v[8:11]
	v_mfma_f32_16x16x32_bf16 v[4:7], v[154:157], v[234:237], v[4:7]
	v_mfma_f32_16x16x32_bf16 v[0:3], v[186:189], v[234:237], v[0:3]
	s_barrier
	s_cbranch_scc0 .LBB0_552
	s_and_b64 vcc, exec, s[14:15]
	s_cbranch_vccz .LBB0_555
	s_barrier

.LBB0_1017:
	s_ashr_i32 s19, s18, 31
	s_lshl_b64 s[20:21], s[18:19], 20
	s_add_u32 s20, s34, s20
	s_addc_u32 s21, s35, s21
	s_and_b64 s[22:23], s[4:5], exec
	s_cselect_b32 s19, s21, s25
	s_cselect_b32 s31, s20, s24
	s_ashr_i32 s17, s16, 31
	s_lshl_b64 s[22:23], s[16:17], 20
	s_add_u32 s22, s36, s22
	s_addc_u32 s23, s37, s23
	s_and_b64 s[28:29], s[4:5], exec
	s_cselect_b32 s17, s23, s27
	s_cselect_b32 s55, s22, s26
	s_add_u32 s24, s24, 0x80080
	s_addc_u32 s25, s25, 0
	s_add_u32 s60, s26, 0x100
	v_mov_b32_e32 v50, 0
	s_addc_u32 s61, s27, 0
	s_mov_b32 s62, -2
	v_mov_b32_e32 v51, v50
	v_mov_b32_e32 v52, v50
	v_mov_b32_e32 v53, v50
	v_mov_b32_e32 v70, v50
	v_mov_b32_e32 v71, v50
	v_mov_b32_e32 v72, v50
	v_mov_b32_e32 v73, v50
	v_mov_b32_e32 v74, v50
	v_mov_b32_e32 v75, v50
	v_mov_b32_e32 v76, v50
	v_mov_b32_e32 v77, v50
	v_mov_b32_e32 v78, v50
	v_mov_b32_e32 v79, v50
	v_mov_b32_e32 v80, v50
	v_mov_b32_e32 v81, v50
	v_mov_b32_e32 v82, v50
	v_mov_b32_e32 v83, v50
	v_mov_b32_e32 v84, v50
	v_mov_b32_e32 v85, v50
	v_mov_b32_e32 v86, v50
	v_mov_b32_e32 v87, v50
	v_mov_b32_e32 v88, v50
	v_mov_b32_e32 v89, v50
	v_mov_b32_e32 v90, v50
	v_mov_b32_e32 v91, v50
	v_mov_b32_e32 v92, v50
	v_mov_b32_e32 v93, v50
	v_mov_b32_e32 v94, v50
	v_mov_b32_e32 v95, v50
	v_mov_b32_e32 v96, v50
	v_mov_b32_e32 v97, v50
	v_mov_b32_e32 v0, v50
	v_mov_b32_e32 v1, v50
	v_mov_b32_e32 v2, v50
	v_mov_b32_e32 v3, v50
	v_mov_b32_e32 v4, v50
	v_mov_b32_e32 v5, v50
	v_mov_b32_e32 v6, v50
	v_mov_b32_e32 v7, v50
	v_mov_b32_e32 v8, v50
	v_mov_b32_e32 v9, v50
	v_mov_b32_e32 v10, v50
	v_mov_b32_e32 v11, v50
	v_mov_b32_e32 v12, v50
	v_mov_b32_e32 v13, v50
	v_mov_b32_e32 v14, v50
	v_mov_b32_e32 v15, v50
	v_mov_b32_e32 v18, v50
	v_mov_b32_e32 v19, v50
	v_mov_b32_e32 v20, v50
	v_mov_b32_e32 v21, v50
	v_mov_b32_e32 v22, v50
	v_mov_b32_e32 v23, v50
	v_mov_b32_e32 v24, v50
	v_mov_b32_e32 v25, v50
	v_mov_b32_e32 v26, v50
	v_mov_b32_e32 v27, v50
	v_mov_b32_e32 v28, v50
	v_mov_b32_e32 v29, v50
	v_mov_b32_e32 v30, v50
	v_mov_b32_e32 v31, v50
	v_mov_b32_e32 v32, v50
	v_mov_b32_e32 v33, v50
	v_mov_b32_e32 v98, v50
	v_mov_b32_e32 v99, v50
	v_mov_b32_e32 v100, v50
	v_mov_b32_e32 v101, v50
	v_mov_b32_e32 v102, v50
	v_mov_b32_e32 v103, v50
	v_mov_b32_e32 v104, v50
	v_mov_b32_e32 v105, v50
	v_mov_b32_e32 v106, v50
	v_mov_b32_e32 v107, v50
	v_mov_b32_e32 v108, v50
	v_mov_b32_e32 v109, v50
	v_mov_b32_e32 v110, v50
	v_mov_b32_e32 v111, v50
	v_mov_b32_e32 v112, v50
	v_mov_b32_e32 v113, v50
	v_mov_b32_e32 v114, v50
	v_mov_b32_e32 v115, v50
	v_mov_b32_e32 v116, v50
	v_mov_b32_e32 v117, v50
	v_mov_b32_e32 v118, v50
	v_mov_b32_e32 v119, v50
	v_mov_b32_e32 v120, v50
	v_mov_b32_e32 v121, v50
	v_mov_b32_e32 v122, v50
	v_mov_b32_e32 v123, v50
	v_mov_b32_e32 v124, v50
	v_mov_b32_e32 v125, v50
	v_mov_b32_e32 v126, v50
	v_mov_b32_e32 v127, v50
	v_mov_b32_e32 v128, v50
	v_mov_b32_e32 v129, v50
	v_mov_b32_e32 v34, v50
	v_mov_b32_e32 v35, v50
	v_mov_b32_e32 v36, v50
	v_mov_b32_e32 v37, v50
	v_mov_b32_e32 v38, v50
	v_mov_b32_e32 v39, v50
	v_mov_b32_e32 v40, v50
	v_mov_b32_e32 v41, v50
	v_mov_b32_e32 v42, v50
	v_mov_b32_e32 v43, v50
	v_mov_b32_e32 v44, v50
	v_mov_b32_e32 v45, v50
	v_mov_b32_e32 v46, v50
	v_mov_b32_e32 v47, v50
	v_mov_b32_e32 v48, v50
	v_mov_b32_e32 v49, v50
	v_mov_b32_e32 v54, v50
	v_mov_b32_e32 v55, v50
	v_mov_b32_e32 v56, v50
	v_mov_b32_e32 v57, v50
	v_mov_b32_e32 v58, v50
	v_mov_b32_e32 v59, v50
	v_mov_b32_e32 v60, v50
	v_mov_b32_e32 v61, v50
	v_mov_b32_e32 v62, v50
	v_mov_b32_e32 v63, v50
	v_mov_b32_e32 v64, v50
	v_mov_b32_e32 v65, v50
	v_mov_b32_e32 v66, v50
	v_mov_b32_e32 v67, v50
	v_mov_b32_e32 v68, v50
	v_mov_b32_e32 v69, v50
	v_add_u32_e32 v168, 0x10000, v166
	v_add_u32_e32 v169, 0x14000, v166
	v_add_u32_e32 v170, 0x18000, v166
	v_add_u32_e32 v171, 0x1c000, v166
	s_add_u32 s26, s24, 0xfff80080
	s_addc_u32 s27, s25, -1
	s_cmp_eq_u32 s62, 28
	s_cselect_b32 s29, s19, s27
	s_cselect_b32 s28, s31, s26
	s_cselect_b32 s27, s17, s61
	s_cselect_b32 s26, s55, s60
.LBB0_1018:
	ds_read_b128 v[144:147], v168
	ds_read_b128 v[148:151], v168 offset:1024
	ds_read_b128 v[152:155], v168 offset:2048
	ds_read_b128 v[156:159], v168 offset:3072
	ds_read_b128 v[160:163], v169
	ds_read_b128 v[176:179], v169 offset:1024
	ds_read_b128 v[180:183], v169 offset:2048
	ds_read_b128 v[184:187], v169 offset:3072
	ds_read_b128 v[188:191], v167
	ds_read_b128 v[192:195], v167 offset:1024
	ds_read_b128 v[196:199], v167 offset:2048
	ds_read_b128 v[200:203], v167 offset:3072
	ds_read_b128 v[204:207], v167 offset:4096
	s_add_i32 m0, s39, 0xc000
	ds_read_b128 v[208:211], v167 offset:5120
	global_load_lds_dwordx4 v140, s[24:25]
	s_add_i32 m0, s39, 0xe000
	ds_read_b128 v[212:215], v167 offset:6144
	global_load_lds_dwordx4 v142, s[24:25]
	ds_read_b128 v[230:233], v167 offset:7168
	s_waitcnt vmcnt(8) lgkmcnt(0)
	s_barrier
	v_mfma_f32_16x16x32_bf16 v[66:69], v[144:147], v[188:191], v[66:69]
	v_mfma_f32_16x16x32_bf16 v[62:65], v[152:155], v[188:191], v[62:65]
	v_mfma_f32_16x16x32_bf16 v[58:61], v[144:147], v[196:199], v[58:61]
	v_mfma_f32_16x16x32_bf16 v[54:57], v[152:155], v[196:199], v[54:57]
	v_mfma_f32_16x16x32_bf16 v[46:49], v[144:147], v[204:207], v[46:49]
	v_mfma_f32_16x16x32_bf16 v[42:45], v[152:155], v[204:207], v[42:45]
	v_mfma_f32_16x16x32_bf16 v[38:41], v[144:147], v[212:215], v[38:41]
	v_mfma_f32_16x16x32_bf16 v[34:37], v[152:155], v[212:215], v[34:37]
	v_mfma_f32_16x16x32_bf16 v[66:69], v[148:151], v[192:195], v[66:69]
	v_mfma_f32_16x16x32_bf16 v[62:65], v[156:159], v[192:195], v[62:65]
	v_mfma_f32_16x16x32_bf16 v[58:61], v[148:151], v[200:203], v[58:61]
	v_mfma_f32_16x16x32_bf16 v[54:57], v[156:159], v[200:203], v[54:57]
	v_mfma_f32_16x16x32_bf16 v[46:49], v[148:151], v[208:211], v[46:49]
	v_mfma_f32_16x16x32_bf16 v[42:45], v[156:159], v[208:211], v[42:45]
	v_mfma_f32_16x16x32_bf16 v[38:41], v[148:151], v[230:233], v[38:41]
	v_mfma_f32_16x16x32_bf16 v[34:37], v[156:159], v[230:233], v[34:37]
	v_mfma_f32_16x16x32_bf16 v[126:129], v[160:163], v[188:191], v[126:129]
	v_mfma_f32_16x16x32_bf16 v[122:125], v[180:183], v[188:191], v[122:125]
	v_mfma_f32_16x16x32_bf16 v[118:121], v[160:163], v[196:199], v[118:121]
	v_mfma_f32_16x16x32_bf16 v[114:117], v[180:183], v[196:199], v[114:117]
	v_mfma_f32_16x16x32_bf16 v[110:113], v[160:163], v[204:207], v[110:113]
	v_mfma_f32_16x16x32_bf16 v[106:109], v[180:183], v[204:207], v[106:109]
	v_mfma_f32_16x16x32_bf16 v[102:105], v[160:163], v[212:215], v[102:105]
	v_mfma_f32_16x16x32_bf16 v[98:101], v[180:183], v[212:215], v[98:101]
	v_mfma_f32_16x16x32_bf16 v[126:129], v[176:179], v[192:195], v[126:129]
	v_mfma_f32_16x16x32_bf16 v[122:125], v[184:187], v[192:195], v[122:125]
	v_mfma_f32_16x16x32_bf16 v[118:121], v[176:179], v[200:203], v[118:121]
	v_mfma_f32_16x16x32_bf16 v[114:117], v[184:187], v[200:203], v[114:117]
	v_mfma_f32_16x16x32_bf16 v[110:113], v[176:179], v[208:211], v[110:113]
	v_mfma_f32_16x16x32_bf16 v[106:109], v[184:187], v[208:211], v[106:109]
	v_mfma_f32_16x16x32_bf16 v[102:105], v[176:179], v[230:233], v[102:105]
	v_mfma_f32_16x16x32_bf16 v[98:101], v[184:187], v[230:233], v[98:101]
	s_barrier
	ds_read_b128 v[188:191], v167 offset:16384
	s_add_i32 m0, s38, 0x10000
	ds_read_b128 v[192:195], v167 offset:17408
	global_load_lds_dwordx4 v132, s[26:27]
	s_add_i32 m0, s38, 0x12000
	s_add_u32 s64, s26, 0x80000
	s_addc_u32 s65, s27, 0
	ds_read_b128 v[196:199], v167 offset:18432
	global_load_lds_dwordx4 v136, s[26:27]
	s_add_i32 m0, s38, 0x14000
	ds_read_b128 v[200:203], v167 offset:19456
	global_load_lds_dwordx4 v132, s[64:65]
	s_add_i32 m0, s38, 0x16000
	ds_read_b128 v[204:207], v167 offset:20480
	global_load_lds_dwordx4 v136, s[64:65]
	s_mov_b32 m0, s39
	ds_read_b128 v[208:211], v167 offset:21504
	global_load_lds_dwordx4 v130, s[28:29]
	s_mov_b32 m0, s40
	ds_read_b128 v[212:215], v167 offset:22528
	global_load_lds_dwordx4 v134, s[28:29]
	ds_read_b128 v[230:233], v167 offset:23552
	s_waitcnt vmcnt(8) lgkmcnt(0)
	s_barrier
	v_mfma_f32_16x16x32_bf16 v[30:33], v[144:147], v[188:191], v[30:33]
	v_mfma_f32_16x16x32_bf16 v[26:29], v[152:155], v[188:191], v[26:29]
	v_mfma_f32_16x16x32_bf16 v[22:25], v[144:147], v[196:199], v[22:25]
	v_mfma_f32_16x16x32_bf16 v[18:21], v[152:155], v[196:199], v[18:21]
	v_mfma_f32_16x16x32_bf16 v[12:15], v[144:147], v[204:207], v[12:15]
	v_mfma_f32_16x16x32_bf16 v[8:11], v[152:155], v[204:207], v[8:11]
	v_mfma_f32_16x16x32_bf16 v[4:7], v[144:147], v[212:215], v[4:7]
	v_mfma_f32_16x16x32_bf16 v[0:3], v[152:155], v[212:215], v[0:3]
	v_mfma_f32_16x16x32_bf16 v[30:33], v[148:151], v[192:195], v[30:33]
	v_mfma_f32_16x16x32_bf16 v[26:29], v[156:159], v[192:195], v[26:29]
	v_mfma_f32_16x16x32_bf16 v[22:25], v[148:151], v[200:203], v[22:25]
	v_mfma_f32_16x16x32_bf16 v[18:21], v[156:159], v[200:203], v[18:21]
	v_mfma_f32_16x16x32_bf16 v[12:15], v[148:151], v[208:211], v[12:15]
	v_mfma_f32_16x16x32_bf16 v[8:11], v[156:159], v[208:211], v[8:11]
	v_mfma_f32_16x16x32_bf16 v[4:7], v[148:151], v[230:233], v[4:7]
	v_mfma_f32_16x16x32_bf16 v[0:3], v[156:159], v[230:233], v[0:3]
	v_mfma_f32_16x16x32_bf16 v[94:97], v[160:163], v[188:191], v[94:97]
	v_mfma_f32_16x16x32_bf16 v[90:93], v[180:183], v[188:191], v[90:93]
	v_mfma_f32_16x16x32_bf16 v[86:89], v[160:163], v[196:199], v[86:89]
	v_mfma_f32_16x16x32_bf16 v[82:85], v[180:183], v[196:199], v[82:85]
	v_mfma_f32_16x16x32_bf16 v[78:81], v[160:163], v[204:207], v[78:81]
	v_mfma_f32_16x16x32_bf16 v[74:77], v[180:183], v[204:207], v[74:77]
	v_mfma_f32_16x16x32_bf16 v[70:73], v[160:163], v[212:215], v[70:73]
	v_mfma_f32_16x16x32_bf16 v[50:53], v[180:183], v[212:215], v[50:53]
	v_mfma_f32_16x16x32_bf16 v[94:97], v[176:179], v[192:195], v[94:97]
	v_mfma_f32_16x16x32_bf16 v[90:93], v[184:187], v[192:195], v[90:93]
	v_mfma_f32_16x16x32_bf16 v[86:89], v[176:179], v[200:203], v[86:89]
	v_mfma_f32_16x16x32_bf16 v[82:85], v[184:187], v[200:203], v[82:85]
	v_mfma_f32_16x16x32_bf16 v[78:81], v[176:179], v[208:211], v[78:81]
	v_mfma_f32_16x16x32_bf16 v[74:77], v[184:187], v[208:211], v[74:77]
	v_mfma_f32_16x16x32_bf16 v[70:73], v[176:179], v[230:233], v[70:73]
	v_mfma_f32_16x16x32_bf16 v[50:53], v[184:187], v[230:233], v[50:53]
	s_barrier
	s_add_u32 s100, s28, 0x80000
	s_addc_u32 s101, s29, 0
	ds_read_b128 v[144:147], v170
	ds_read_b128 v[148:151], v170 offset:1024
	ds_read_b128 v[152:155], v170 offset:2048
	ds_read_b128 v[156:159], v170 offset:3072
	ds_read_b128 v[160:163], v171
	ds_read_b128 v[176:179], v171 offset:1024
	ds_read_b128 v[180:183], v171 offset:2048
	ds_read_b128 v[184:187], v171 offset:3072
	ds_read_b128 v[188:191], v167 offset:32768
	ds_read_b128 v[192:195], v167 offset:33792
	ds_read_b128 v[196:199], v167 offset:34816
	ds_read_b128 v[200:203], v167 offset:35840
	ds_read_b128 v[204:207], v167 offset:36864
	s_mov_b32 m0, s41
	ds_read_b128 v[208:211], v167 offset:37888
	global_load_lds_dwordx4 v130, s[100:101]
	s_mov_b32 m0, s42
	ds_read_b128 v[212:215], v167 offset:38912
	global_load_lds_dwordx4 v134, s[100:101]
	ds_read_b128 v[230:233], v167 offset:39936
	s_waitcnt vmcnt(8) lgkmcnt(0)
	s_barrier
	v_mfma_f32_16x16x32_bf16 v[66:69], v[144:147], v[188:191], v[66:69]
	v_mfma_f32_16x16x32_bf16 v[62:65], v[152:155], v[188:191], v[62:65]
	v_mfma_f32_16x16x32_bf16 v[58:61], v[144:147], v[196:199], v[58:61]
	v_mfma_f32_16x16x32_bf16 v[54:57], v[152:155], v[196:199], v[54:57]
	v_mfma_f32_16x16x32_bf16 v[46:49], v[144:147], v[204:207], v[46:49]
	v_mfma_f32_16x16x32_bf16 v[42:45], v[152:155], v[204:207], v[42:45]
	v_mfma_f32_16x16x32_bf16 v[38:41], v[144:147], v[212:215], v[38:41]
	v_mfma_f32_16x16x32_bf16 v[34:37], v[152:155], v[212:215], v[34:37]
	v_mfma_f32_16x16x32_bf16 v[66:69], v[148:151], v[192:195], v[66:69]
	v_mfma_f32_16x16x32_bf16 v[62:65], v[156:159], v[192:195], v[62:65]
	v_mfma_f32_16x16x32_bf16 v[58:61], v[148:151], v[200:203], v[58:61]
	v_mfma_f32_16x16x32_bf16 v[54:57], v[156:159], v[200:203], v[54:57]
	v_mfma_f32_16x16x32_bf16 v[46:49], v[148:151], v[208:211], v[46:49]
	v_mfma_f32_16x16x32_bf16 v[42:45], v[156:159], v[208:211], v[42:45]
	v_mfma_f32_16x16x32_bf16 v[38:41], v[148:151], v[230:233], v[38:41]
	v_mfma_f32_16x16x32_bf16 v[34:37], v[156:159], v[230:233], v[34:37]
	v_mfma_f32_16x16x32_bf16 v[126:129], v[160:163], v[188:191], v[126:129]
	v_mfma_f32_16x16x32_bf16 v[122:125], v[180:183], v[188:191], v[122:125]
	v_mfma_f32_16x16x32_bf16 v[118:121], v[160:163], v[196:199], v[118:121]
	v_mfma_f32_16x16x32_bf16 v[114:117], v[180:183], v[196:199], v[114:117]
	v_mfma_f32_16x16x32_bf16 v[110:113], v[160:163], v[204:207], v[110:113]
	v_mfma_f32_16x16x32_bf16 v[106:109], v[180:183], v[204:207], v[106:109]
	v_mfma_f32_16x16x32_bf16 v[102:105], v[160:163], v[212:215], v[102:105]
	v_mfma_f32_16x16x32_bf16 v[98:101], v[180:183], v[212:215], v[98:101]
	v_mfma_f32_16x16x32_bf16 v[126:129], v[176:179], v[192:195], v[126:129]
	v_mfma_f32_16x16x32_bf16 v[122:125], v[184:187], v[192:195], v[122:125]
	v_mfma_f32_16x16x32_bf16 v[118:121], v[176:179], v[200:203], v[118:121]
	v_mfma_f32_16x16x32_bf16 v[114:117], v[184:187], v[200:203], v[114:117]
	v_mfma_f32_16x16x32_bf16 v[110:113], v[176:179], v[208:211], v[110:113]
	v_mfma_f32_16x16x32_bf16 v[106:109], v[184:187], v[208:211], v[106:109]
	v_mfma_f32_16x16x32_bf16 v[102:105], v[176:179], v[230:233], v[102:105]
	v_mfma_f32_16x16x32_bf16 v[98:101], v[184:187], v[230:233], v[98:101]
	s_barrier
	ds_read_b128 v[188:191], v167 offset:49152
	s_add_i32 m0, s38, 0x17f80
	ds_read_b128 v[192:195], v167 offset:50176
	global_load_lds_dwordx4 v132, s[26:27] offset:128
	s_add_i32 m0, s38, 0x19f80
	ds_read_b128 v[196:199], v167 offset:51200
	global_load_lds_dwordx4 v136, s[26:27] offset:128
	s_add_i32 m0, s38, 0x1bf80
	ds_read_b128 v[200:203], v167 offset:52224
	global_load_lds_dwordx4 v132, s[64:65] offset:128
	s_add_i32 m0, s38, 0x1df80
	ds_read_b128 v[204:207], v167 offset:53248
	global_load_lds_dwordx4 v136, s[64:65] offset:128
	s_add_i32 m0, s46, 0xffffff80
	ds_read_b128 v[208:211], v167 offset:54272
	global_load_lds_dwordx4 v130, s[28:29] offset:128
	s_add_i32 m0, s47, 0xffffff80
	ds_read_b128 v[212:215], v167 offset:55296
	global_load_lds_dwordx4 v134, s[28:29] offset:128
	ds_read_b128 v[230:233], v167 offset:56320
	s_add_i32 s62, s62, 2
	s_add_u32 s24, s24, 0x100
	s_addc_u32 s25, s25, 0
	s_add_u32 s60, s60, 0x100
	s_addc_u32 s61, s61, 0
	s_add_u32 s26, s24, 0xfff80080
	s_addc_u32 s27, s25, -1
	s_cmp_eq_u32 s62, 28
	s_cselect_b32 s29, s19, s27
	s_cselect_b32 s28, s31, s26
	s_cselect_b32 s27, s17, s61
	s_cselect_b32 s26, s55, s60
	s_cmp_gt_u32 s62, 29
	s_waitcnt vmcnt(8) lgkmcnt(0)
	s_barrier
	v_mfma_f32_16x16x32_bf16 v[30:33], v[144:147], v[188:191], v[30:33]
	v_mfma_f32_16x16x32_bf16 v[26:29], v[152:155], v[188:191], v[26:29]
	v_mfma_f32_16x16x32_bf16 v[22:25], v[144:147], v[196:199], v[22:25]
	v_mfma_f32_16x16x32_bf16 v[18:21], v[152:155], v[196:199], v[18:21]
	v_mfma_f32_16x16x32_bf16 v[12:15], v[144:147], v[204:207], v[12:15]
	v_mfma_f32_16x16x32_bf16 v[8:11], v[152:155], v[204:207], v[8:11]
	v_mfma_f32_16x16x32_bf16 v[4:7], v[144:147], v[212:215], v[4:7]
	v_mfma_f32_16x16x32_bf16 v[0:3], v[152:155], v[212:215], v[0:3]
	v_mfma_f32_16x16x32_bf16 v[30:33], v[148:151], v[192:195], v[30:33]
	v_mfma_f32_16x16x32_bf16 v[26:29], v[156:159], v[192:195], v[26:29]
	v_mfma_f32_16x16x32_bf16 v[22:25], v[148:151], v[200:203], v[22:25]
	v_mfma_f32_16x16x32_bf16 v[18:21], v[156:159], v[200:203], v[18:21]
	v_mfma_f32_16x16x32_bf16 v[12:15], v[148:151], v[208:211], v[12:15]
	v_mfma_f32_16x16x32_bf16 v[8:11], v[156:159], v[208:211], v[8:11]
	v_mfma_f32_16x16x32_bf16 v[4:7], v[148:151], v[230:233], v[4:7]
	v_mfma_f32_16x16x32_bf16 v[0:3], v[156:159], v[230:233], v[0:3]
	v_mfma_f32_16x16x32_bf16 v[94:97], v[160:163], v[188:191], v[94:97]
	v_mfma_f32_16x16x32_bf16 v[90:93], v[180:183], v[188:191], v[90:93]
	v_mfma_f32_16x16x32_bf16 v[86:89], v[160:163], v[196:199], v[86:89]
	v_mfma_f32_16x16x32_bf16 v[82:85], v[180:183], v[196:199], v[82:85]
	v_mfma_f32_16x16x32_bf16 v[78:81], v[160:163], v[204:207], v[78:81]
	v_mfma_f32_16x16x32_bf16 v[74:77], v[180:183], v[204:207], v[74:77]
	v_mfma_f32_16x16x32_bf16 v[70:73], v[160:163], v[212:215], v[70:73]
	v_mfma_f32_16x16x32_bf16 v[50:53], v[180:183], v[212:215], v[50:53]
	v_mfma_f32_16x16x32_bf16 v[94:97], v[176:179], v[192:195], v[94:97]
	v_mfma_f32_16x16x32_bf16 v[90:93], v[184:187], v[192:195], v[90:93]
	v_mfma_f32_16x16x32_bf16 v[86:89], v[176:179], v[200:203], v[86:89]
	v_mfma_f32_16x16x32_bf16 v[82:85], v[184:187], v[200:203], v[82:85]
	v_mfma_f32_16x16x32_bf16 v[78:81], v[176:179], v[208:211], v[78:81]
	v_mfma_f32_16x16x32_bf16 v[74:77], v[184:187], v[208:211], v[74:77]
	v_mfma_f32_16x16x32_bf16 v[70:73], v[176:179], v[230:233], v[70:73]
	v_mfma_f32_16x16x32_bf16 v[50:53], v[184:187], v[230:233], v[50:53]
	s_barrier
	s_cbranch_scc0 .LBB0_1018
	s_and_b64 vcc, exec, s[8:9]
	s_cbranch_vccz .LBB0_1021
	s_barrier
